# v30 + non-temporal (nt) hint on the weight-prep phase's streaming f32 weight loads
# speedup vs baseline: 1.0069x; 1.0069x over previous
; #define ARGP(i) ka_ptr(ka, (i) * 8)
; __global__ void __launch_bounds__(NWAVES * 64, 2) fwd_kernel(Args args_unused) {
;     ...
;             if (r >= 16) { const int t = r - 16; float gvv; if (t == 0) gvv = ARGP(I_QNA)[lane]; else if (t == 1) gvv = ARGP(I_KNA)[lane]; else if (t == 2) gvv = ARGP(I_QNB)[lane]; else gvv = ARGP(I_KNB)[lane];
;                 ((float*)(ws + WS_GAINS))[t * 64 + lane] = gvv; continue; }
.LBB0_55:
	s_waitcnt lgkmcnt(4)
	v_lshl_add_u64 v[34:35], v[0:1], 2, s[12:13]
	global_load_dword v6, v[34:35], off nt
	v_lshl_add_u32 v34, s90, 6, v108
	v_ashrrev_i32_e32 v35, 31, v34
	v_lshl_add_u64 v[34:35], v[34:35], 2, s[38:39]
	s_mov_b64 s[12:13], 0
	s_waitcnt vmcnt(0)
	global_store_dword v[34:35], v6, off
	s_branch .LBB0_58

; #define ARGP(i) ka_ptr(ka, (i) * 8)
; __global__ void __launch_bounds__(NWAVES * 64, 2) fwd_kernel(Args args_unused) {
;     ...
;             if (r == 20) {
;                 float ga = fabsf(ARGP(I_QNA)[lane]), gb = fabsf(ARGP(I_KNA)[lane]), gc = fabsf(ARGP(I_QNB)[lane]), gd = fabsf(ARGP(I_KNB)[lane]), rm = 0.f;
;                 const float* rp = ARGP(I_RPB);
;                 for (int idx = lane; idx < 8 * 465; idx += 64) rm = fmaxf(rm, fabsf(rp[idx]));
; #pragma unroll
;                 for (int o = 1; o < 64; o <<= 1) { ga = fmaxf(ga, __shfl_xor(ga, o)); gb = fmaxf(gb, __shfl_xor(gb, o)); gc = fmaxf(gc, __shfl_xor(gc, o)); gd = fmaxf(gd, __shfl_xor(gd, o)); rm = fmaxf(rm, __shfl_xor(rm, o)); }
;                 if (lane == 0) { float* bd = (float*)(ws + WS_BOUNDS); bd[0] = 64.0f * C2 * ga * gb * 1.02f; bd[1] = 64.0f * C2 * gc * gd * 1.02f + rm * LOG2E; }
.LBB0_58:
	s_andn2_b64 vcc, exec, s[12:13]
	s_cbranch_vccnz .LBB0_74
	s_waitcnt lgkmcnt(4)
	v_lshlrev_b64 v[34:35], 2, v[0:1]
	s_load_dwordx2 s[12:13], s[96:97], 64
	s_waitcnt lgkmcnt(0)
	s_waitcnt lgkmcnt(1)
	v_mov_b32_e32 v39, 0
	v_lshl_add_u64 v[36:37], s[12:13], 0, v[34:35]
	global_load_dword v38, v[36:37], off nt
	s_load_dwordx2 s[12:13], s[96:97], 0x48
	s_waitcnt lgkmcnt(0)
	s_nop 0
	v_lshl_add_u64 v[36:37], s[12:13], 0, v[34:35]
	global_load_dword v33, v[36:37], off nt
	s_load_dwordx2 s[12:13], s[96:97], 0x58
	s_waitcnt lgkmcnt(0)
	s_nop 0
	v_lshl_add_u64 v[36:37], s[12:13], 0, v[34:35]
	global_load_dword v6, v[36:37], off nt
	s_load_dwordx2 s[12:13], s[96:97], 0x60
	s_waitcnt lgkmcnt(0)
	s_nop 0
	v_lshl_add_u64 v[34:35], s[12:13], 0, v[34:35]
	global_load_dword v31, v[34:35], off nt
	s_load_dwordx2 s[18:19], s[96:97], 0x68
	s_waitcnt lgkmcnt(0)
	s_and_saveexec_b64 s[14:15], s[16:17]
	s_cbranch_execz .LBB0_71
	s_mov_b64 s[60:61], -1
	s_waitcnt lgkmcnt(0)
	v_mov_b32_e32 v40, 0
	v_mov_b32_e32 v34, v0
	v_mov_b64_e32 v[36:37], v[0:1]
	s_and_saveexec_b64 s[20:21], s[8:9]
	s_cbranch_execz .LBB0_66
	v_mov_b32_e32 v39, 0
	s_mov_b32 s34, 2
	s_mov_b64 s[62:63], 0
	v_mov_b64_e32 v[34:35], v[18:19]
	v_mov_b32_e32 v40, 0
.LBB0_62:
	v_ashrrev_i32_e32 v37, 31, v35
	v_mov_b32_e32 v36, v35
	v_ashrrev_i32_e32 v43, 31, v34
	v_mov_b32_e32 v42, v34
	v_lshl_add_u64 v[42:43], v[42:43], 2, s[18:19]
	v_lshl_add_u64 v[36:37], v[36:37], 2, s[18:19]
	global_load_dword v44, v[36:37], off nt
	s_nop 0
	global_load_dword v42, v[42:43], off nt
	v_mov_b32_e32 v36, v39
	v_mov_b32_e32 v37, v40
	v_max_f32_e32 v39, v37, v37
	v_max_f32_e32 v43, v36, v36
	v_cmp_eq_u32_e32 vcc, s34, v115
	s_add_i32 s34, s34, 2
	v_add_u32_e32 v35, 0x80, v35
	v_add_u32_e32 v34, 0x80, v34
	v_mov_b32_e32 v41, s34
	s_waitcnt vmcnt(1)
	v_cmp_u_f32_e64 s[12:13], v44, v44
	v_max_f32_e64 v40, |v44|, |v44|
	s_waitcnt vmcnt(0)
	v_max_f32_e64 v45, |v42|, |v42|
	v_cndmask_b32_e64 v44, 0, 1, s[12:13]
	v_cmp_u_f32_e64 s[12:13], v42, v42
	v_max_f32_e32 v40, v39, v40
	v_max_f32_e32 v39, v43, v45
	v_cndmask_b32_e64 v42, 0, 1, s[12:13]
	v_lshlrev_b16_e32 v43, 1, v44
	v_bitop3_b16 v42, v42, 3, v43 bitop3:0xc8
	v_cmp_ne_u16_e64 s[12:13], 0, v42
	s_or_b64 s[92:93], s[12:13], vcc
	s_and_b64 s[92:93], exec, s[92:93]
	s_or_b64 s[62:63], s[92:93], s[62:63]
	s_andn2_b64 s[60:61], s[60:61], exec
	s_and_b64 s[12:13], s[12:13], exec
	s_or_b64 s[60:61], s[60:61], s[12:13]
	s_andn2_b64 exec, exec, s[62:63]
	s_cbranch_execnz .LBB0_62
	s_or_b64 exec, exec, s[62:63]
	v_cndmask_b32_e64 v34, v39, v36, s[60:61]
	v_cndmask_b32_e64 v35, v40, v37, s[60:61]
	v_max_f32_e32 v35, v35, v35
	v_max_f32_e32 v34, v34, v34
	v_max_f32_e32 v39, v34, v35
	s_or_b64 s[92:93], s[10:11], s[60:61]
	s_mov_b64 s[12:13], 0
	v_mov_b32_e32 v40, 0
	s_and_saveexec_b64 s[62:63], s[92:93]
	v_add_u32_e32 v34, -4, v41
	v_cndmask_b32_e64 v34, v115, v34, s[60:61]
	v_lshl_add_u32 v34, v34, 6, v0
	v_ashrrev_i32_e32 v35, 31, v34
	s_mov_b64 s[12:13], exec
	v_mov_b32_e32 v40, v39
	v_mov_b64_e32 v[36:37], v[34:35]
	s_or_b64 exec, exec, s[62:63]
	s_orn2_b64 s[60:61], s[12:13], exec

; #define ARGP(i) ka_ptr(ka, (i) * 8)
; __global__ void __launch_bounds__(NWAVES * 64, 2) fwd_kernel(Args args_unused) {
;     ...
;                 const float* rp = ARGP(I_RPB);
;                 for (int idx = lane; idx < 8 * 465; idx += 64) rm = fmaxf(rm, fabsf(rp[idx]));
.LBB0_68:
	global_load_dword v36, v[34:35], off nt
	v_add_u32_e32 v39, 64, v39
	s_movk_i32 s34, 0xe47
	v_max_f32_e32 v37, v40, v40
	s_mov_b64 s[20:21], 0x100
	v_cmp_lt_i32_e32 vcc, s34, v39
	v_lshl_add_u64 v[34:35], v[34:35], 0, s[20:21]
	s_or_b64 s[18:19], vcc, s[18:19]
	s_waitcnt vmcnt(0)
	v_max_f32_e64 v36, |v36|, |v36|
	v_max_f32_e32 v40, v37, v36
	s_andn2_b64 exec, exec, s[18:19]
	s_cbranch_execnz .LBB0_68
	s_or_b64 exec, exec, s[18:19]
	v_mov_b32_e32 v39, v40

; template <int MODE>
; __device__ __forceinline__ void transpose_item(const float* __restrict__ W, int K, int N, bf16_t* __restrict__ WT, LAS float* scr, int item, int lane, const float* __restrict__ ga, const float* __restrict__ gb) {
;     const int nblk = N / 32, kb = item / nblk, nb = item % nblk, k0 = 64 * kb, n0 = 32 * nb;
; #pragma unroll 8
;     for (int i = 0; i < 32; ++i) { const int kk = 2 * i + (lane >> 5); float v = W[(size_t)(k0 + kk) * N + n0 + (lane & 31)];
;         if (MODE == 1) { const int k = k0 + kk; v *= (k < 512) ? ga[k] : gb[k - 512]; }
;         scr[kk * 33 + (lane & 31)] = v; }
.LBB0_77:
	s_lshl_b32 s19, s15, 1
	s_lshl_b32 s20, s13, 1
	v_add_u32_e32 v52, s19, v6
	v_add_u32_e32 v50, s20, v31
	v_add_u32_e32 v54, s20, v33
	v_add_u32_e32 v56, s19, v36
	v_add_u32_e32 v58, s20, v37
	v_add_u32_e32 v60, s19, v38
	v_add_u32_e32 v62, s20, v39
	v_add_u32_e32 v64, s19, v40
	v_add_u32_e32 v66, s20, v41
	v_add_u32_e32 v68, s19, v42
	v_add_u32_e32 v70, s20, v43
	v_add_u32_e32 v72, s19, v44
	v_add_u32_e32 v74, s20, v45
	v_add_u32_e32 v76, s19, v46
	v_add_u32_e32 v78, s20, v47
	v_add_u32_e32 v80, s19, v48
	v_ashrrev_i32_e32 v53, 31, v52
	v_ashrrev_i32_e32 v51, 31, v50
	v_ashrrev_i32_e32 v57, 31, v56
	v_ashrrev_i32_e32 v55, 31, v54
	v_ashrrev_i32_e32 v61, 31, v60
	v_ashrrev_i32_e32 v59, 31, v58
	v_ashrrev_i32_e32 v65, 31, v64
	v_ashrrev_i32_e32 v63, 31, v62
	v_ashrrev_i32_e32 v69, 31, v68
	v_ashrrev_i32_e32 v67, 31, v66
	v_ashrrev_i32_e32 v73, 31, v72
	v_ashrrev_i32_e32 v71, 31, v70
	v_ashrrev_i32_e32 v77, 31, v76
	v_ashrrev_i32_e32 v75, 31, v74
	v_ashrrev_i32_e32 v81, 31, v80
	v_ashrrev_i32_e32 v79, 31, v78
	v_lshlrev_b64 v[52:53], 12, v[52:53]
	v_lshlrev_b64 v[50:51], 12, v[50:51]
	v_lshlrev_b64 v[54:55], 12, v[54:55]
	v_lshlrev_b64 v[56:57], 12, v[56:57]
	v_lshlrev_b64 v[58:59], 12, v[58:59]
	v_lshlrev_b64 v[60:61], 12, v[60:61]
	v_lshlrev_b64 v[62:63], 12, v[62:63]
	v_lshlrev_b64 v[64:65], 12, v[64:65]
	v_lshlrev_b64 v[66:67], 12, v[66:67]
	v_lshlrev_b64 v[68:69], 12, v[68:69]
	v_lshlrev_b64 v[70:71], 12, v[70:71]
	v_lshlrev_b64 v[72:73], 12, v[72:73]
	v_lshlrev_b64 v[74:75], 12, v[74:75]
	v_lshlrev_b64 v[76:77], 12, v[76:77]
	v_lshlrev_b64 v[78:79], 12, v[78:79]
	v_lshlrev_b64 v[80:81], 12, v[80:81]
	v_lshl_add_u64 v[52:53], v[34:35], 0, v[52:53]
	v_lshl_add_u64 v[50:51], v[34:35], 0, v[50:51]
	v_lshl_add_u64 v[56:57], v[34:35], 0, v[56:57]
	v_lshl_add_u64 v[54:55], v[34:35], 0, v[54:55]
	v_lshl_add_u64 v[60:61], v[34:35], 0, v[60:61]
	v_lshl_add_u64 v[58:59], v[34:35], 0, v[58:59]
	v_lshl_add_u64 v[64:65], v[34:35], 0, v[64:65]
	v_lshl_add_u64 v[62:63], v[34:35], 0, v[62:63]
	v_lshl_add_u64 v[68:69], v[34:35], 0, v[68:69]
	v_lshl_add_u64 v[66:67], v[34:35], 0, v[66:67]
	v_lshl_add_u64 v[72:73], v[34:35], 0, v[72:73]
	v_lshl_add_u64 v[70:71], v[34:35], 0, v[70:71]
	v_lshl_add_u64 v[76:77], v[34:35], 0, v[76:77]
	v_lshl_add_u64 v[74:75], v[34:35], 0, v[74:75]
	v_lshl_add_u64 v[80:81], v[34:35], 0, v[80:81]
	v_lshl_add_u64 v[78:79], v[34:35], 0, v[78:79]
	global_load_dword v82, v[52:53], off nt
	global_load_dword v83, v[50:51], off nt
	global_load_dword v84, v[56:57], off nt
	global_load_dword v85, v[54:55], off nt
	global_load_dword v86, v[60:61], off nt
	global_load_dword v87, v[58:59], off nt
	global_load_dword v88, v[64:65], off nt
	global_load_dword v89, v[62:63], off nt
	global_load_dword v90, v[68:69], off nt
	global_load_dword v91, v[66:67], off nt
	global_load_dword v92, v[72:73], off nt
	global_load_dword v93, v[70:71], off nt
	global_load_dword v94, v[76:77], off nt
	global_load_dword v95, v[74:75], off nt
	global_load_dword v96, v[80:81], off nt
	global_load_dword v97, v[78:79], off nt
	s_add_i32 s15, s15, 16
	s_add_i32 s13, s13, 16
	s_add_i32 s18, s18, -16
	v_add_u32_e32 v50, s19, v2
	v_add_u32_e32 v52, s20, v3
	v_add_u32_e32 v56, s20, v5
	v_add_u32_e32 v54, s19, v20
	v_add_u32_e32 v60, s20, v9
	v_add_u32_e32 v58, s19, v22
	v_add_u32_e32 v64, s20, v21
	v_add_u32_e32 v62, s19, v24
	v_add_u32_e32 v68, s20, v23
	v_add_u32_e32 v66, s19, v26
	v_add_u32_e32 v72, s20, v25
	v_add_u32_e32 v70, s19, v28
	v_add_u32_e32 v76, s20, v27
	v_add_u32_e32 v74, s19, v30
	v_add_u32_e32 v80, s20, v29
	v_add_u32_e32 v78, s19, v32
	s_cmp_lg_u32 s18, 0
	v_mad_u64_u32 v[50:51], s[20:21], v50, s1, v[8:9]
	v_mad_u64_u32 v[52:53], s[20:21], v52, s1, v[8:9]
	v_mad_u64_u32 v[54:55], s[20:21], v54, s1, v[8:9]
	v_mad_u64_u32 v[56:57], s[20:21], v56, s1, v[8:9]
	v_mad_u64_u32 v[58:59], s[20:21], v58, s1, v[8:9]
	v_mad_u64_u32 v[60:61], s[20:21], v60, s1, v[8:9]
	v_mad_u64_u32 v[62:63], s[20:21], v62, s1, v[8:9]
	v_mad_u64_u32 v[64:65], s[20:21], v64, s1, v[8:9]
	v_mad_u64_u32 v[66:67], s[20:21], v66, s1, v[8:9]
	v_mad_u64_u32 v[68:69], s[20:21], v68, s1, v[8:9]
	v_mad_u64_u32 v[70:71], s[20:21], v70, s1, v[8:9]
	v_mad_u64_u32 v[72:73], s[20:21], v72, s1, v[8:9]
	v_mad_u64_u32 v[74:75], s[20:21], v74, s1, v[8:9]
	v_mad_u64_u32 v[76:77], s[20:21], v76, s1, v[8:9]
	v_mad_u64_u32 v[78:79], s[20:21], v78, s1, v[8:9]
	v_mad_u64_u32 v[80:81], s[20:21], v80, s1, v[8:9]
	s_waitcnt vmcnt(15)
	ds_write_b32 v50, v82
	s_waitcnt vmcnt(14)
	ds_write_b32 v52, v83
	s_waitcnt vmcnt(13)
	ds_write_b32 v54, v84
	s_waitcnt vmcnt(12)
	ds_write_b32 v56, v85
	s_waitcnt vmcnt(11)
	ds_write_b32 v58, v86
	s_waitcnt vmcnt(10)
	ds_write_b32 v60, v87
	s_waitcnt vmcnt(9)
	ds_write_b32 v62, v88
	s_waitcnt vmcnt(8)
	ds_write_b32 v64, v89
	s_waitcnt vmcnt(7)
	ds_write_b32 v66, v90
	s_waitcnt vmcnt(6)
	ds_write_b32 v68, v91
	s_waitcnt vmcnt(5)
	ds_write_b32 v70, v92
	s_waitcnt vmcnt(4)
	ds_write_b32 v72, v93
	s_waitcnt vmcnt(3)
	ds_write_b32 v74, v94
	s_waitcnt vmcnt(2)
	ds_write_b32 v76, v95
	s_waitcnt vmcnt(1)
	ds_write_b32 v78, v96
	s_waitcnt vmcnt(0)
	ds_write_b32 v80, v97
	s_cbranch_scc1 .LBB0_77
; #define LAS __attribute__((address_space(3)))
; __device__ __forceinline__ unsigned cvtpk(float lo, float hi) { f32x2 v = {lo, hi}; bf16x2_t b = __builtin_convertvector(v, bf16x2_t); return __builtin_bit_cast(unsigned, b); }
; template <int MODE>
; __device__ __forceinline__ void transpose_item(const float* __restrict__ W, int K, int N, bf16_t* __restrict__ WT, LAS float* scr, int item, int lane, const float* __restrict__ ga, const float* __restrict__ gb) {
;     ...
;     asm volatile("s_waitcnt lgkmcnt(0)" ::: "memory");
;     const int c = lane & 7;
; #pragma unroll
;     for (int j = 0; j < 4; ++j) { const int n = (lane >> 3) + 8 * j; const LAS float* s = scr + (8 * c) * 33 + n;
;         u32x4 o; o.x = cvtpk(s[0 * 33], s[1 * 33]); o.y = cvtpk(s[2 * 33], s[3 * 33]); o.z = cvtpk(s[4 * 33], s[5 * 33]); o.w = cvtpk(s[6 * 33], s[7 * 33]);
;         const int nn = n0 + n; int drow = nn;
;         if (MODE == 2) drow = 256 * (nn >> 7) + (nn & 127);
;         if (MODE == 3) drow = 256 * (nn >> 7) + 128 + (nn & 127);
;         *(u32x4*)(WT + (size_t)drow * K + k0 + 8 * c) = o; }
;     asm volatile("s_waitcnt lgkmcnt(0)" ::: "memory");
	s_waitcnt lgkmcnt(0)
	ds_read2_b32 v[38:39], v110 offset0:33 offset1:41
	ds_read2_b32 v[40:41], v110 offset1:8
	ds_read2_b32 v[42:43], v110 offset0:66 offset1:74
	ds_read2_b32 v[44:45], v110 offset0:99 offset1:107
	ds_read2_b32 v[46:47], v110 offset0:132 offset1:140
	ds_read2_b32 v[50:51], v110 offset0:165 offset1:173
	ds_read2_b32 v[52:53], v110 offset0:198 offset1:206
	ds_read2_b32 v[54:55], v110 offset0:231 offset1:239
	s_and_b32 s14, 0xffff, s14
	s_lshl_b32 s34, s12, 1
	v_lshl_add_u64 v[56:57], v[10:11], 0, s[34:35]
	v_add_u32_e32 v6, s14, v109
	s_waitcnt lgkmcnt(6)
	v_cvt_pk_bf16_f32 v34, v40, v38
	s_waitcnt lgkmcnt(4)
	v_cvt_pk_bf16_f32 v35, v42, v44
	s_waitcnt lgkmcnt(2)
	v_cvt_pk_bf16_f32 v36, v46, v50
	s_waitcnt lgkmcnt(0)
	v_cvt_pk_bf16_f32 v37, v52, v54
	v_mad_i64_i32 v[58:59], s[12:13], v6, s72, v[56:57]
	global_store_dwordx4 v[58:59], v[34:37], off sc1
	v_add_u32_e32 v6, s14, v111
	s_nop 0
	v_cvt_pk_bf16_f32 v34, v41, v39
	v_cvt_pk_bf16_f32 v35, v43, v45
	v_cvt_pk_bf16_f32 v36, v47, v51
	v_cvt_pk_bf16_f32 v37, v53, v55
	ds_read2_b32 v[40:41], v110 offset0:49 offset1:57
	ds_read2_b32 v[42:43], v110 offset0:16 offset1:24
	ds_read2_b32 v[44:45], v110 offset0:82 offset1:90
	ds_read2_b32 v[46:47], v110 offset0:115 offset1:123
	ds_read2_b32 v[50:51], v110 offset0:148 offset1:156
	ds_read2_b32 v[52:53], v110 offset0:181 offset1:189
	ds_read2_b32 v[54:55], v110 offset0:214 offset1:222
	ds_read2_b32 v[58:59], v110 offset0:247 offset1:255
	v_mad_i64_i32 v[38:39], s[12:13], v6, s72, v[56:57]
	v_add_u32_e32 v6, s14, v112
	global_store_dwordx4 v[38:39], v[34:37], off sc1
	v_mad_i64_i32 v[38:39], s[12:13], v6, s72, v[56:57]
	s_waitcnt lgkmcnt(6)
	v_cvt_pk_bf16_f32 v34, v42, v40
	s_waitcnt lgkmcnt(4)
	v_cvt_pk_bf16_f32 v35, v44, v46
	s_waitcnt lgkmcnt(2)
	v_cvt_pk_bf16_f32 v36, v50, v52
	s_waitcnt lgkmcnt(0)
	v_cvt_pk_bf16_f32 v37, v54, v58
	v_add_u32_e32 v6, s14, v113
	global_store_dwordx4 v[38:39], v[34:37], off sc1
	v_mad_i64_i32 v[38:39], s[12:13], v6, s72, v[56:57]
	s_nop 0
	v_cvt_pk_bf16_f32 v34, v43, v41
	v_cvt_pk_bf16_f32 v35, v45, v47
	v_cvt_pk_bf16_f32 v36, v51, v53
	v_cvt_pk_bf16_f32 v37, v55, v59
	global_store_dwordx4 v[38:39], v[34:37], off sc1
	s_waitcnt lgkmcnt(0)

; template <int MODE>
; __device__ __forceinline__ void transpose_item(const float* __restrict__ W, int K, int N, bf16_t* __restrict__ WT, LAS float* scr, int item, int lane, const float* __restrict__ ga, const float* __restrict__ gb) {
;     const int nblk = N / 32, kb = item / nblk, nb = item % nblk, k0 = 64 * kb, n0 = 32 * nb;
; #pragma unroll 8
;     for (int i = 0; i < 32; ++i) { const int kk = 2 * i + (lane >> 5); float v = W[(size_t)(k0 + kk) * N + n0 + (lane & 31)];
;         if (MODE == 1) { const int k = k0 + kk; v *= (k < 512) ? ga[k] : gb[k - 512]; }
;         scr[kk * 33 + (lane & 31)] = v; }
.LBB0_82:
	s_lshl_b32 s19, s15, 1
	s_lshl_b32 s34, s14, 1
	v_add_u32_e32 v50, s19, v6
	v_add_u32_e32 v52, s34, v31
	v_add_u32_e32 v56, s34, v33
	v_add_u32_e32 v54, s19, v36
	v_add_u32_e32 v60, s34, v37
	v_add_u32_e32 v58, s19, v38
	v_add_u32_e32 v64, s34, v39
	v_add_u32_e32 v62, s19, v40
	v_add_u32_e32 v68, s34, v41
	v_add_u32_e32 v66, s19, v42
	v_add_u32_e32 v72, s34, v43
	v_add_u32_e32 v70, s19, v44
	v_add_u32_e32 v76, s34, v45
	v_add_u32_e32 v74, s19, v46
	v_add_u32_e32 v80, s34, v47
	v_add_u32_e32 v78, s19, v48
	v_mad_i64_i32 v[50:51], s[20:21], v50, s73, v[34:35]
	v_mad_i64_i32 v[52:53], s[20:21], v52, s73, v[34:35]
	v_mad_i64_i32 v[54:55], s[20:21], v54, s73, v[34:35]
	v_mad_i64_i32 v[56:57], s[20:21], v56, s73, v[34:35]
	v_mad_i64_i32 v[58:59], s[20:21], v58, s73, v[34:35]
	v_mad_i64_i32 v[60:61], s[20:21], v60, s73, v[34:35]
	v_mad_i64_i32 v[62:63], s[20:21], v62, s73, v[34:35]
	v_mad_i64_i32 v[64:65], s[20:21], v64, s73, v[34:35]
	v_mad_i64_i32 v[66:67], s[20:21], v66, s73, v[34:35]
	v_mad_i64_i32 v[68:69], s[20:21], v68, s73, v[34:35]
	v_mad_i64_i32 v[70:71], s[20:21], v70, s73, v[34:35]
	v_mad_i64_i32 v[72:73], s[20:21], v72, s73, v[34:35]
	v_mad_i64_i32 v[74:75], s[20:21], v74, s73, v[34:35]
	v_mad_i64_i32 v[76:77], s[20:21], v76, s73, v[34:35]
	v_mad_i64_i32 v[78:79], s[20:21], v78, s73, v[34:35]
	v_mad_i64_i32 v[80:81], s[20:21], v80, s73, v[34:35]
	global_load_dword v82, v[50:51], off nt
	global_load_dword v83, v[52:53], off nt
	global_load_dword v84, v[54:55], off nt
	global_load_dword v85, v[56:57], off nt
	global_load_dword v86, v[58:59], off nt
	global_load_dword v87, v[60:61], off nt
	global_load_dword v88, v[62:63], off nt
	global_load_dword v89, v[64:65], off nt
	global_load_dword v90, v[66:67], off nt
	global_load_dword v91, v[68:69], off nt
	global_load_dword v92, v[70:71], off nt
	global_load_dword v93, v[72:73], off nt
	global_load_dword v94, v[74:75], off nt
	global_load_dword v95, v[76:77], off nt
	global_load_dword v96, v[78:79], off nt
	global_load_dword v97, v[80:81], off nt
	s_add_i32 s15, s15, 16
	s_add_i32 s14, s14, 16
	s_add_i32 s18, s18, -16
	v_add_u32_e32 v50, s19, v2
	v_add_u32_e32 v52, s34, v3
	v_add_u32_e32 v56, s34, v5
	v_add_u32_e32 v54, s19, v20
	v_add_u32_e32 v60, s34, v9
	v_add_u32_e32 v58, s19, v22
	v_add_u32_e32 v64, s34, v21
	v_add_u32_e32 v62, s19, v24
	v_add_u32_e32 v68, s34, v23
	v_add_u32_e32 v66, s19, v26
	v_add_u32_e32 v72, s34, v25
	v_add_u32_e32 v70, s19, v28
	v_add_u32_e32 v76, s34, v27
	v_add_u32_e32 v74, s19, v30
	v_add_u32_e32 v80, s34, v29
	v_add_u32_e32 v78, s19, v32
	s_cmp_lg_u32 s18, 0
	v_mad_u64_u32 v[50:51], s[20:21], v50, s1, v[8:9]
	v_mad_u64_u32 v[52:53], s[20:21], v52, s1, v[8:9]
	v_mad_u64_u32 v[54:55], s[20:21], v54, s1, v[8:9]
	v_mad_u64_u32 v[56:57], s[20:21], v56, s1, v[8:9]
	v_mad_u64_u32 v[58:59], s[20:21], v58, s1, v[8:9]
	v_mad_u64_u32 v[60:61], s[20:21], v60, s1, v[8:9]
	v_mad_u64_u32 v[62:63], s[20:21], v62, s1, v[8:9]
	v_mad_u64_u32 v[64:65], s[20:21], v64, s1, v[8:9]
	v_mad_u64_u32 v[66:67], s[20:21], v66, s1, v[8:9]
	v_mad_u64_u32 v[68:69], s[20:21], v68, s1, v[8:9]
	v_mad_u64_u32 v[70:71], s[20:21], v70, s1, v[8:9]
	v_mad_u64_u32 v[72:73], s[20:21], v72, s1, v[8:9]
	v_mad_u64_u32 v[74:75], s[20:21], v74, s1, v[8:9]
	v_mad_u64_u32 v[76:77], s[20:21], v76, s1, v[8:9]
	v_mad_u64_u32 v[78:79], s[20:21], v78, s1, v[8:9]
	v_mad_u64_u32 v[80:81], s[20:21], v80, s1, v[8:9]
	s_waitcnt vmcnt(15)
	ds_write_b32 v50, v82
	s_waitcnt vmcnt(14)
	ds_write_b32 v52, v83
	s_waitcnt vmcnt(13)
	ds_write_b32 v54, v84
	s_waitcnt vmcnt(12)
	ds_write_b32 v56, v85
	s_waitcnt vmcnt(11)
	ds_write_b32 v58, v86
	s_waitcnt vmcnt(10)
	ds_write_b32 v60, v87
	s_waitcnt vmcnt(9)
	ds_write_b32 v62, v88
	s_waitcnt vmcnt(8)
	ds_write_b32 v64, v89
	s_waitcnt vmcnt(7)
	ds_write_b32 v66, v90
	s_waitcnt vmcnt(6)
	ds_write_b32 v68, v91
	s_waitcnt vmcnt(5)
	ds_write_b32 v70, v92
	s_waitcnt vmcnt(4)
	ds_write_b32 v72, v93
	s_waitcnt vmcnt(3)
	ds_write_b32 v74, v94
	s_waitcnt vmcnt(2)
	ds_write_b32 v76, v95
	s_waitcnt vmcnt(1)
	ds_write_b32 v78, v96
	s_waitcnt vmcnt(0)
	ds_write_b32 v80, v97
	s_cbranch_scc1 .LBB0_82
; #define LAS __attribute__((address_space(3)))
; __device__ __forceinline__ unsigned cvtpk(float lo, float hi) { f32x2 v = {lo, hi}; bf16x2_t b = __builtin_convertvector(v, bf16x2_t); return __builtin_bit_cast(unsigned, b); }
; template <int MODE>
; __device__ __forceinline__ void transpose_item(const float* __restrict__ W, int K, int N, bf16_t* __restrict__ WT, LAS float* scr, int item, int lane, const float* __restrict__ ga, const float* __restrict__ gb) {
;     ...
;     asm volatile("s_waitcnt lgkmcnt(0)" ::: "memory");
;     const int c = lane & 7;
; #pragma unroll
;     for (int j = 0; j < 4; ++j) { const int n = (lane >> 3) + 8 * j; const LAS float* s = scr + (8 * c) * 33 + n;
;         u32x4 o; o.x = cvtpk(s[0 * 33], s[1 * 33]); o.y = cvtpk(s[2 * 33], s[3 * 33]); o.z = cvtpk(s[4 * 33], s[5 * 33]); o.w = cvtpk(s[6 * 33], s[7 * 33]);
;         const int nn = n0 + n; int drow = nn;
;         if (MODE == 2) drow = 256 * (nn >> 7) + (nn & 127);
;         if (MODE == 3) drow = 256 * (nn >> 7) + 128 + (nn & 127);
;         *(u32x4*)(WT + (size_t)drow * K + k0 + 8 * c) = o; }
;     asm volatile("s_waitcnt lgkmcnt(0)" ::: "memory");
	s_and_b32 s13, 0xffff, s13
	s_waitcnt lgkmcnt(0)
	v_add_u32_e32 v6, s13, v109
	ds_read2_b32 v[38:39], v110 offset0:33 offset1:41
	ds_read2_b32 v[40:41], v110 offset1:8
	ds_read2_b32 v[42:43], v110 offset0:66 offset1:74
	ds_read2_b32 v[44:45], v110 offset0:99 offset1:107
	ds_read2_b32 v[46:47], v110 offset0:132 offset1:140
	ds_read2_b32 v[50:51], v110 offset0:165 offset1:173
	ds_read2_b32 v[52:53], v110 offset0:198 offset1:206
	ds_read2_b32 v[54:55], v110 offset0:231 offset1:239
	v_lshlrev_b32_e32 v31, 1, v6
	v_and_b32_e32 v31, 0xffffff00, v31
	v_and_b32_e32 v6, 0x7f, v6
	s_and_b32 s12, 0xffff, s12
	v_or3_b32 v58, v6, v31, s71
	v_add_u32_e32 v6, s13, v111
	s_lshl_b32 s34, s12, 1
	v_ashrrev_i32_e32 v59, 31, v58
	v_lshlrev_b32_e32 v31, 1, v6
	v_lshl_add_u64 v[56:57], v[12:13], 0, s[34:35]
	v_lshlrev_b64 v[58:59], 11, v[58:59]
	v_and_b32_e32 v31, 0xffffff00, v31
	v_and_b32_e32 v6, 0x7f, v6
	s_waitcnt lgkmcnt(6)
	v_cvt_pk_bf16_f32 v34, v40, v38
	s_waitcnt lgkmcnt(4)
	v_cvt_pk_bf16_f32 v35, v42, v44
	s_waitcnt lgkmcnt(2)
	v_cvt_pk_bf16_f32 v36, v46, v50
	s_waitcnt lgkmcnt(0)
	v_cvt_pk_bf16_f32 v37, v52, v54
	v_lshl_add_u64 v[58:59], v[56:57], 0, v[58:59]
	v_or3_b32 v38, v6, v31, s71
	global_store_dwordx4 v[58:59], v[34:37], off sc1
	v_add_u32_e32 v6, s13, v112
	v_lshlrev_b32_e32 v31, 1, v6
	v_cvt_pk_bf16_f32 v34, v41, v39
	v_ashrrev_i32_e32 v39, 31, v38
	v_cvt_pk_bf16_f32 v35, v43, v45
	v_cvt_pk_bf16_f32 v36, v47, v51
	v_cvt_pk_bf16_f32 v37, v53, v55
	v_lshlrev_b64 v[38:39], 11, v[38:39]
	ds_read2_b32 v[40:41], v110 offset0:16 offset1:24
	ds_read2_b32 v[42:43], v110 offset0:49 offset1:57
	ds_read2_b32 v[44:45], v110 offset0:82 offset1:90
	ds_read2_b32 v[46:47], v110 offset0:115 offset1:123
	ds_read2_b32 v[50:51], v110 offset0:148 offset1:156
	ds_read2_b32 v[52:53], v110 offset0:181 offset1:189
	ds_read2_b32 v[54:55], v110 offset0:214 offset1:222
	ds_read2_b32 v[58:59], v110 offset0:247 offset1:255
	v_lshl_add_u64 v[38:39], v[56:57], 0, v[38:39]
	v_and_b32_e32 v31, 0xffffff00, v31
	v_and_b32_e32 v6, 0x7f, v6
	global_store_dwordx4 v[38:39], v[34:37], off sc1
	v_or3_b32 v38, v6, v31, s71
	v_ashrrev_i32_e32 v39, 31, v38
	v_add_u32_e32 v6, s13, v113
	v_lshlrev_b64 v[38:39], 11, v[38:39]
	v_lshlrev_b32_e32 v31, 1, v6
	s_waitcnt lgkmcnt(6)
	v_cvt_pk_bf16_f32 v34, v40, v42
	s_waitcnt lgkmcnt(4)
	v_cvt_pk_bf16_f32 v35, v44, v46
	s_waitcnt lgkmcnt(2)
	v_cvt_pk_bf16_f32 v36, v50, v52
	s_waitcnt lgkmcnt(0)
	v_cvt_pk_bf16_f32 v37, v54, v58
	v_lshl_add_u64 v[38:39], v[56:57], 0, v[38:39]
	v_and_b32_e32 v31, 0xffffff00, v31
	v_and_b32_e32 v6, 0x7f, v6
	global_store_dwordx4 v[38:39], v[34:37], off sc1
	v_or3_b32 v38, v6, v31, s71
	v_ashrrev_i32_e32 v39, 31, v38
	v_lshlrev_b64 v[38:39], 11, v[38:39]
	v_cvt_pk_bf16_f32 v34, v41, v43
	v_cvt_pk_bf16_f32 v35, v45, v47
	v_cvt_pk_bf16_f32 v36, v51, v53
	v_cvt_pk_bf16_f32 v37, v55, v59
	v_lshl_add_u64 v[38:39], v[56:57], 0, v[38:39]
	global_store_dwordx4 v[38:39], v[34:37], off sc1
	s_waitcnt lgkmcnt(0)

; #define LAS __attribute__((address_space(3)))
; __device__ __forceinline__ unsigned cvtpk(float lo, float hi) { f32x2 v = {lo, hi}; bf16x2_t b = __builtin_convertvector(v, bf16x2_t); return __builtin_bit_cast(unsigned, b); }
; template <int MODE>
; __device__ __forceinline__ void transpose_item(const float* __restrict__ W, int K, int N, bf16_t* __restrict__ WT, LAS float* scr, int item, int lane, const float* __restrict__ ga, const float* __restrict__ gb) {
;     const int nblk = N / 32, kb = item / nblk, nb = item % nblk, k0 = 64 * kb, n0 = 32 * nb;
; #pragma unroll 8
;     for (int i = 0; i < 32; ++i) { const int kk = 2 * i + (lane >> 5); float v = W[(size_t)(k0 + kk) * N + n0 + (lane & 31)];
;         if (MODE == 1) { const int k = k0 + kk; v *= (k < 512) ? ga[k] : gb[k - 512]; }
;         scr[kk * 33 + (lane & 31)] = v; }
;     asm volatile("s_waitcnt lgkmcnt(0)" ::: "memory");
;     const int c = lane & 7;
; #pragma unroll
;     for (int j = 0; j < 4; ++j) { const int n = (lane >> 3) + 8 * j; const LAS float* s = scr + (8 * c) * 33 + n;
;         u32x4 o; o.x = cvtpk(s[0 * 33], s[1 * 33]); o.y = cvtpk(s[2 * 33], s[3 * 33]); o.z = cvtpk(s[4 * 33], s[5 * 33]); o.w = cvtpk(s[6 * 33], s[7 * 33]);
;         const int nn = n0 + n; int drow = nn;
;         if (MODE == 2) drow = 256 * (nn >> 7) + (nn & 127);
;         if (MODE == 3) drow = 256 * (nn >> 7) + 128 + (nn & 127);
;         *(u32x4*)(WT + (size_t)drow * K + k0 + 8 * c) = o; }
;     asm volatile("s_waitcnt lgkmcnt(0)" ::: "memory");
.LBB0_87:
	s_lshl_b32 s19, s15, 1
	s_lshl_b32 s34, s14, 1
	v_add_u32_e32 v50, s19, v6
	v_add_u32_e32 v52, s34, v31
	v_add_u32_e32 v56, s34, v33
	v_add_u32_e32 v54, s19, v36
	v_add_u32_e32 v60, s34, v37
	v_add_u32_e32 v58, s19, v38
	v_add_u32_e32 v64, s34, v39
	v_add_u32_e32 v62, s19, v40
	v_add_u32_e32 v68, s34, v41
	v_add_u32_e32 v66, s19, v42
	v_add_u32_e32 v72, s34, v43
	v_add_u32_e32 v70, s19, v44
	v_add_u32_e32 v76, s34, v45
	v_add_u32_e32 v74, s19, v46
	v_add_u32_e32 v80, s34, v47
	v_add_u32_e32 v78, s19, v48
	v_mad_i64_i32 v[50:51], s[20:21], v50, s73, v[34:35]
	v_mad_i64_i32 v[52:53], s[20:21], v52, s73, v[34:35]
	v_mad_i64_i32 v[54:55], s[20:21], v54, s73, v[34:35]
	v_mad_i64_i32 v[56:57], s[20:21], v56, s73, v[34:35]
	v_mad_i64_i32 v[58:59], s[20:21], v58, s73, v[34:35]
	v_mad_i64_i32 v[60:61], s[20:21], v60, s73, v[34:35]
	v_mad_i64_i32 v[62:63], s[20:21], v62, s73, v[34:35]
	v_mad_i64_i32 v[64:65], s[20:21], v64, s73, v[34:35]
	v_mad_i64_i32 v[66:67], s[20:21], v66, s73, v[34:35]
	v_mad_i64_i32 v[68:69], s[20:21], v68, s73, v[34:35]
	v_mad_i64_i32 v[70:71], s[20:21], v70, s73, v[34:35]
	v_mad_i64_i32 v[72:73], s[20:21], v72, s73, v[34:35]
	v_mad_i64_i32 v[74:75], s[20:21], v74, s73, v[34:35]
	v_mad_i64_i32 v[76:77], s[20:21], v76, s73, v[34:35]
	v_mad_i64_i32 v[78:79], s[20:21], v78, s73, v[34:35]
	v_mad_i64_i32 v[80:81], s[20:21], v80, s73, v[34:35]
	global_load_dword v82, v[50:51], off nt
	global_load_dword v83, v[52:53], off nt
	global_load_dword v84, v[54:55], off nt
	global_load_dword v85, v[56:57], off nt
	global_load_dword v86, v[58:59], off nt
	global_load_dword v87, v[60:61], off nt
	global_load_dword v88, v[62:63], off nt
	global_load_dword v89, v[64:65], off nt
	global_load_dword v90, v[66:67], off nt
	global_load_dword v91, v[68:69], off nt
	global_load_dword v92, v[70:71], off nt
	global_load_dword v93, v[72:73], off nt
	global_load_dword v94, v[74:75], off nt
	global_load_dword v95, v[76:77], off nt
	global_load_dword v96, v[78:79], off nt
	global_load_dword v97, v[80:81], off nt
	s_add_i32 s15, s15, 16
	s_add_i32 s14, s14, 16
	s_add_i32 s18, s18, -16
	v_add_u32_e32 v50, s19, v2
	v_add_u32_e32 v52, s34, v3
	v_add_u32_e32 v56, s34, v5
	v_add_u32_e32 v54, s19, v20
	v_add_u32_e32 v60, s34, v9
	v_add_u32_e32 v58, s19, v22
	v_add_u32_e32 v64, s34, v21
	v_add_u32_e32 v62, s19, v24
	v_add_u32_e32 v68, s34, v23
	v_add_u32_e32 v66, s19, v26
	v_add_u32_e32 v72, s34, v25
	v_add_u32_e32 v70, s19, v28
	v_add_u32_e32 v76, s34, v27
	v_add_u32_e32 v74, s19, v30
	v_add_u32_e32 v80, s34, v29
	v_add_u32_e32 v78, s19, v32
	s_cmp_lg_u32 s18, 0
	v_mad_u64_u32 v[50:51], s[20:21], v50, s1, v[8:9]
	v_mad_u64_u32 v[52:53], s[20:21], v52, s1, v[8:9]
	v_mad_u64_u32 v[54:55], s[20:21], v54, s1, v[8:9]
	v_mad_u64_u32 v[56:57], s[20:21], v56, s1, v[8:9]
	v_mad_u64_u32 v[58:59], s[20:21], v58, s1, v[8:9]
	v_mad_u64_u32 v[60:61], s[20:21], v60, s1, v[8:9]
	v_mad_u64_u32 v[62:63], s[20:21], v62, s1, v[8:9]
	v_mad_u64_u32 v[64:65], s[20:21], v64, s1, v[8:9]
	v_mad_u64_u32 v[66:67], s[20:21], v66, s1, v[8:9]
	v_mad_u64_u32 v[68:69], s[20:21], v68, s1, v[8:9]
	v_mad_u64_u32 v[70:71], s[20:21], v70, s1, v[8:9]
	v_mad_u64_u32 v[72:73], s[20:21], v72, s1, v[8:9]
	v_mad_u64_u32 v[74:75], s[20:21], v74, s1, v[8:9]
	v_mad_u64_u32 v[76:77], s[20:21], v76, s1, v[8:9]
	v_mad_u64_u32 v[78:79], s[20:21], v78, s1, v[8:9]
	v_mad_u64_u32 v[80:81], s[20:21], v80, s1, v[8:9]
	s_waitcnt vmcnt(15)
	ds_write_b32 v50, v82
	s_waitcnt vmcnt(14)
	ds_write_b32 v52, v83
	s_waitcnt vmcnt(13)
	ds_write_b32 v54, v84
	s_waitcnt vmcnt(12)
	ds_write_b32 v56, v85
	s_waitcnt vmcnt(11)
	ds_write_b32 v58, v86
	s_waitcnt vmcnt(10)
	ds_write_b32 v60, v87
	s_waitcnt vmcnt(9)
	ds_write_b32 v62, v88
	s_waitcnt vmcnt(8)
	ds_write_b32 v64, v89
	s_waitcnt vmcnt(7)
	ds_write_b32 v66, v90
	s_waitcnt vmcnt(6)
	ds_write_b32 v68, v91
	s_waitcnt vmcnt(5)
	ds_write_b32 v70, v92
	s_waitcnt vmcnt(4)
	ds_write_b32 v72, v93
	s_waitcnt vmcnt(3)
	ds_write_b32 v74, v94
	s_waitcnt vmcnt(2)
	ds_write_b32 v76, v95
	s_waitcnt vmcnt(1)
	ds_write_b32 v78, v96
	s_waitcnt vmcnt(0)
	ds_write_b32 v80, v97
	s_cbranch_scc1 .LBB0_87
	s_and_b32 s13, 0xffff, s13
	s_waitcnt lgkmcnt(0)
	ds_read2_b32 v[38:39], v110 offset0:33 offset1:41
	ds_read2_b32 v[40:41], v110 offset1:8
	ds_read2_b32 v[42:43], v110 offset0:66 offset1:74
	ds_read2_b32 v[44:45], v110 offset0:99 offset1:107
	ds_read2_b32 v[46:47], v110 offset0:132 offset1:140
	ds_read2_b32 v[50:51], v110 offset0:165 offset1:173
	ds_read2_b32 v[52:53], v110 offset0:198 offset1:206
	ds_read2_b32 v[54:55], v110 offset0:231 offset1:239
	v_add_u32_e32 v6, s13, v109
	v_lshlrev_b32_e32 v31, 1, v6
	v_and_b32_e32 v6, 0x7f, v6
	s_and_b32 s12, 0xffff, s12
	v_and_or_b32 v58, v31, s74, v6
	s_lshl_b32 s34, s12, 1
	v_ashrrev_i32_e32 v59, 31, v58
	v_add_u32_e32 v6, s13, v111
	v_lshl_add_u64 v[56:57], v[12:13], 0, s[34:35]
	v_lshlrev_b64 v[58:59], 11, v[58:59]
	v_lshlrev_b32_e32 v31, 1, v6
	v_and_b32_e32 v6, 0x7f, v6
	s_waitcnt lgkmcnt(6)
	v_cvt_pk_bf16_f32 v34, v40, v38
	s_waitcnt lgkmcnt(4)
	v_cvt_pk_bf16_f32 v35, v42, v44
	s_waitcnt lgkmcnt(2)
	v_cvt_pk_bf16_f32 v36, v46, v50
	s_waitcnt lgkmcnt(0)
	v_cvt_pk_bf16_f32 v37, v52, v54
	v_lshl_add_u64 v[58:59], v[56:57], 0, v[58:59]
	v_and_or_b32 v38, v31, s74, v6
	global_store_dwordx4 v[58:59], v[34:37], off sc1
	v_add_u32_e32 v6, s13, v112
	v_lshlrev_b32_e32 v31, 1, v6
	v_cvt_pk_bf16_f32 v34, v41, v39
	v_ashrrev_i32_e32 v39, 31, v38
	v_cvt_pk_bf16_f32 v35, v43, v45
	v_cvt_pk_bf16_f32 v36, v47, v51
	v_cvt_pk_bf16_f32 v37, v53, v55
	v_lshlrev_b64 v[38:39], 11, v[38:39]
	ds_read2_b32 v[40:41], v110 offset0:16 offset1:24
	ds_read2_b32 v[42:43], v110 offset0:49 offset1:57
	ds_read2_b32 v[44:45], v110 offset0:82 offset1:90
	ds_read2_b32 v[46:47], v110 offset0:115 offset1:123
	ds_read2_b32 v[50:51], v110 offset0:148 offset1:156
	ds_read2_b32 v[52:53], v110 offset0:181 offset1:189
	ds_read2_b32 v[54:55], v110 offset0:214 offset1:222
	ds_read2_b32 v[58:59], v110 offset0:247 offset1:255
	v_lshl_add_u64 v[38:39], v[56:57], 0, v[38:39]
	v_and_b32_e32 v6, 0x7f, v6
	global_store_dwordx4 v[38:39], v[34:37], off sc1
	v_and_or_b32 v38, v31, s74, v6
	v_ashrrev_i32_e32 v39, 31, v38
	v_lshlrev_b64 v[38:39], 11, v[38:39]
	v_add_u32_e32 v6, s13, v113
	s_waitcnt lgkmcnt(6)
	v_cvt_pk_bf16_f32 v34, v40, v42
	s_waitcnt lgkmcnt(4)
	v_cvt_pk_bf16_f32 v35, v44, v46
	s_waitcnt lgkmcnt(2)
	v_cvt_pk_bf16_f32 v36, v50, v52
	s_waitcnt lgkmcnt(0)
	v_cvt_pk_bf16_f32 v37, v54, v58
	v_lshl_add_u64 v[38:39], v[56:57], 0, v[38:39]
	v_lshlrev_b32_e32 v31, 1, v6
	v_and_b32_e32 v6, 0x7f, v6
	global_store_dwordx4 v[38:39], v[34:37], off sc1
	v_and_or_b32 v38, v31, s74, v6
	v_ashrrev_i32_e32 v39, 31, v38
	v_lshlrev_b64 v[38:39], 11, v[38:39]
	v_cvt_pk_bf16_f32 v34, v41, v43
	v_cvt_pk_bf16_f32 v35, v45, v47
	v_cvt_pk_bf16_f32 v36, v51, v53
	v_cvt_pk_bf16_f32 v37, v55, v59
	v_lshl_add_u64 v[38:39], v[56:57], 0, v[38:39]
	global_store_dwordx4 v[38:39], v[34:37], off sc1
	s_waitcnt lgkmcnt(0)

; template <int MODE>
; __device__ __forceinline__ void transpose_item(const float* __restrict__ W, int K, int N, bf16_t* __restrict__ WT, LAS float* scr, int item, int lane, const float* __restrict__ ga, const float* __restrict__ gb) {
;     const int nblk = N / 32, kb = item / nblk, nb = item % nblk, k0 = 64 * kb, n0 = 32 * nb;
; #pragma unroll 8
;     for (int i = 0; i < 32; ++i) { const int kk = 2 * i + (lane >> 5); float v = W[(size_t)(k0 + kk) * N + n0 + (lane & 31)];
;         if (MODE == 1) { const int k = k0 + kk; v *= (k < 512) ? ga[k] : gb[k - 512]; }
;         scr[kk * 33 + (lane & 31)] = v; }
.LBB0_92:
	s_lshl_b32 s92, s61, 1
	v_add_u32_e32 v86, s92, v31
	s_lshl_b32 s91, s62, 1
	v_ashrrev_i32_e32 v87, 31, v86
	v_add_u32_e32 v84, s91, v6
	v_lshlrev_b64 v[50:51], 2, v[86:87]
	v_ashrrev_i32_e32 v85, 31, v84
	v_lshl_add_u64 v[102:103], s[18:19], 0, v[50:51]
	v_lshl_add_u64 v[50:51], s[20:21], 0, v[50:51]
	v_add_u32_e32 v78, s92, v33
	v_lshlrev_b64 v[52:53], 2, v[84:85]
	v_lshl_add_u64 v[50:51], v[50:51], 0, s[58:59]
	v_cmp_gt_i32_e32 vcc, s75, v86
	v_ashrrev_i32_e32 v79, 31, v78
	v_add_u32_e32 v76, s91, v36
	v_cndmask_b32_e32 v51, v51, v103, vcc
	v_cndmask_b32_e32 v50, v50, v102, vcc
	v_lshl_add_u64 v[102:103], s[18:19], 0, v[52:53]
	v_lshl_add_u64 v[52:53], s[20:21], 0, v[52:53]
	v_lshlrev_b64 v[54:55], 2, v[78:79]
	v_lshl_add_u64 v[52:53], v[52:53], 0, s[58:59]
	v_cmp_gt_i32_e32 vcc, s75, v84
	v_ashrrev_i32_e32 v77, 31, v76
	v_add_u32_e32 v82, s92, v37
	v_cndmask_b32_e32 v53, v53, v103, vcc
	v_cndmask_b32_e32 v52, v52, v102, vcc
	v_lshl_add_u64 v[102:103], s[18:19], 0, v[54:55]
	v_lshl_add_u64 v[54:55], s[20:21], 0, v[54:55]
	v_lshlrev_b64 v[56:57], 2, v[76:77]
	v_lshl_add_u64 v[54:55], v[54:55], 0, s[58:59]
	v_cmp_gt_i32_e32 vcc, s75, v78
	v_ashrrev_i32_e32 v83, 31, v82
	v_add_u32_e32 v80, s91, v38
	v_cndmask_b32_e32 v55, v55, v103, vcc
	v_cndmask_b32_e32 v54, v54, v102, vcc
	v_lshl_add_u64 v[102:103], s[18:19], 0, v[56:57]
	v_lshl_add_u64 v[56:57], s[20:21], 0, v[56:57]
	v_lshlrev_b64 v[58:59], 2, v[82:83]
	v_lshl_add_u64 v[56:57], v[56:57], 0, s[58:59]
	v_cmp_gt_i32_e32 vcc, s75, v76
	v_ashrrev_i32_e32 v81, 31, v80
	v_add_u32_e32 v90, s92, v39
	v_cndmask_b32_e32 v57, v57, v103, vcc
	v_cndmask_b32_e32 v56, v56, v102, vcc
	v_lshl_add_u64 v[102:103], s[18:19], 0, v[58:59]
	v_lshl_add_u64 v[58:59], s[20:21], 0, v[58:59]
	v_lshlrev_b64 v[60:61], 2, v[80:81]
	v_lshl_add_u64 v[58:59], v[58:59], 0, s[58:59]
	v_cmp_gt_i32_e32 vcc, s75, v82
	v_ashrrev_i32_e32 v91, 31, v90
	v_add_u32_e32 v88, s91, v40
	v_cndmask_b32_e32 v59, v59, v103, vcc
	v_cndmask_b32_e32 v58, v58, v102, vcc
	v_lshl_add_u64 v[102:103], s[18:19], 0, v[60:61]
	v_lshl_add_u64 v[60:61], s[20:21], 0, v[60:61]
	v_lshlrev_b64 v[62:63], 2, v[90:91]
	v_lshl_add_u64 v[60:61], v[60:61], 0, s[58:59]
	v_cmp_gt_i32_e32 vcc, s75, v80
	v_ashrrev_i32_e32 v89, 31, v88
	v_add_u32_e32 v94, s92, v41
	v_cndmask_b32_e32 v61, v61, v103, vcc
	v_cndmask_b32_e32 v60, v60, v102, vcc
	v_lshl_add_u64 v[102:103], s[18:19], 0, v[62:63]
	v_lshl_add_u64 v[62:63], s[20:21], 0, v[62:63]
	v_lshlrev_b64 v[64:65], 2, v[88:89]
	v_lshl_add_u64 v[62:63], v[62:63], 0, s[58:59]
	v_cmp_gt_i32_e32 vcc, s75, v90
	v_ashrrev_i32_e32 v95, 31, v94
	v_add_u32_e32 v92, s91, v42
	v_cndmask_b32_e32 v63, v63, v103, vcc
	v_cndmask_b32_e32 v62, v62, v102, vcc
	v_lshl_add_u64 v[102:103], s[18:19], 0, v[64:65]
	v_lshl_add_u64 v[64:65], s[20:21], 0, v[64:65]
	v_lshlrev_b64 v[66:67], 2, v[94:95]
	v_lshl_add_u64 v[64:65], v[64:65], 0, s[58:59]
	v_cmp_gt_i32_e32 vcc, s75, v88
	v_ashrrev_i32_e32 v93, 31, v92
	v_add_u32_e32 v98, s92, v43
	v_cndmask_b32_e32 v65, v65, v103, vcc
	v_cndmask_b32_e32 v64, v64, v102, vcc
	v_lshl_add_u64 v[102:103], s[18:19], 0, v[66:67]
	v_lshl_add_u64 v[66:67], s[20:21], 0, v[66:67]
	v_lshlrev_b64 v[68:69], 2, v[92:93]
	v_lshl_add_u64 v[66:67], v[66:67], 0, s[58:59]
	v_cmp_gt_i32_e32 vcc, s75, v94
	v_ashrrev_i32_e32 v99, 31, v98
	v_add_u32_e32 v96, s91, v44
	v_cndmask_b32_e32 v67, v67, v103, vcc
	v_cndmask_b32_e32 v66, v66, v102, vcc
	v_lshl_add_u64 v[102:103], s[18:19], 0, v[68:69]
	v_lshl_add_u64 v[68:69], s[20:21], 0, v[68:69]
	v_lshlrev_b64 v[70:71], 2, v[98:99]
	v_lshl_add_u64 v[68:69], v[68:69], 0, s[58:59]
	v_cmp_gt_i32_e32 vcc, s75, v92
	v_ashrrev_i32_e32 v97, 31, v96
	v_add_u32_e32 v100, s92, v45
	v_cndmask_b32_e32 v69, v69, v103, vcc
	v_cndmask_b32_e32 v68, v68, v102, vcc
	v_lshl_add_u64 v[102:103], s[18:19], 0, v[70:71]
	v_lshl_add_u64 v[70:71], s[20:21], 0, v[70:71]
	v_lshlrev_b64 v[72:73], 2, v[96:97]
	v_lshl_add_u64 v[70:71], v[70:71], 0, s[58:59]
	v_cmp_gt_i32_e32 vcc, s75, v98
	v_ashrrev_i32_e32 v101, 31, v100
	v_lshlrev_b64 v[74:75], 2, v[100:101]
	v_cndmask_b32_e32 v71, v71, v103, vcc
	v_cndmask_b32_e32 v70, v70, v102, vcc
	v_lshl_add_u64 v[102:103], s[18:19], 0, v[72:73]
	v_lshl_add_u64 v[72:73], s[20:21], 0, v[72:73]
	v_lshl_add_u64 v[72:73], v[72:73], 0, s[58:59]
	v_cmp_gt_i32_e32 vcc, s75, v96
	v_lshlrev_b64 v[86:87], 12, v[86:87]
	v_lshlrev_b64 v[84:85], 12, v[84:85]
	v_lshlrev_b64 v[78:79], 12, v[78:79]
	v_lshlrev_b64 v[76:77], 12, v[76:77]
	v_cndmask_b32_e32 v73, v73, v103, vcc
	v_cndmask_b32_e32 v72, v72, v102, vcc
	v_lshl_add_u64 v[102:103], s[18:19], 0, v[74:75]
	v_lshl_add_u64 v[74:75], s[20:21], 0, v[74:75]
	v_lshl_add_u64 v[84:85], v[34:35], 0, v[84:85]
	v_lshl_add_u64 v[86:87], v[34:35], 0, v[86:87]
	v_lshlrev_b64 v[82:83], 12, v[82:83]
	v_lshlrev_b64 v[80:81], 12, v[80:81]
	v_lshl_add_u64 v[76:77], v[34:35], 0, v[76:77]
	v_lshl_add_u64 v[78:79], v[34:35], 0, v[78:79]
	v_lshl_add_u64 v[74:75], v[74:75], 0, s[58:59]
	v_cmp_gt_i32_e32 vcc, s75, v100
	global_load_dword v84, v[84:85], off nt
	s_nop 0
	global_load_dword v85, v[86:87], off nt
	v_lshlrev_b64 v[86:87], 12, v[90:91]
	v_lshlrev_b64 v[88:89], 12, v[88:89]
	global_load_dword v76, v[76:77], off nt
	s_nop 0
	global_load_dword v77, v[78:79], off nt
	v_lshl_add_u64 v[78:79], v[34:35], 0, v[80:81]
	v_lshl_add_u64 v[80:81], v[34:35], 0, v[82:83]
	v_cndmask_b32_e32 v74, v74, v102, vcc
	v_add_u32_e32 v102, s91, v46
	v_lshlrev_b64 v[90:91], 12, v[94:95]
	v_lshlrev_b64 v[92:93], 12, v[92:93]
	global_load_dword v78, v[78:79], off nt
	s_nop 0
	global_load_dword v79, v[80:81], off nt
	v_lshl_add_u64 v[80:81], v[34:35], 0, v[88:89]
; template <int MODE>
; __device__ __forceinline__ void transpose_item(const float* __restrict__ W, int K, int N, bf16_t* __restrict__ WT, LAS float* scr, int item, int lane, const float* __restrict__ ga, const float* __restrict__ gb) {
;     const int nblk = N / 32, kb = item / nblk, nb = item % nblk, k0 = 64 * kb, n0 = 32 * nb;
; #pragma unroll 8
;     for (int i = 0; i < 32; ++i) { const int kk = 2 * i + (lane >> 5); float v = W[(size_t)(k0 + kk) * N + n0 + (lane & 31)];
;         if (MODE == 1) { const int k = k0 + kk; v *= (k < 512) ? ga[k] : gb[k - 512]; }
;         scr[kk * 33 + (lane & 31)] = v; }
	v_lshl_add_u64 v[86:87], v[34:35], 0, v[86:87]
	v_cndmask_b32_e32 v75, v75, v103, vcc
	v_add_u32_e32 v104, s92, v47
	v_add_u32_e32 v106, s91, v48
	v_ashrrev_i32_e32 v103, 31, v102
	v_lshlrev_b64 v[94:95], 12, v[98:99]
	v_lshlrev_b64 v[96:97], 12, v[96:97]
	global_load_dword v82, v[80:81], off nt
	global_load_dword v83, v[86:87], off nt
	v_lshl_add_u64 v[80:81], v[34:35], 0, v[92:93]
	v_lshl_add_u64 v[86:87], v[34:35], 0, v[90:91]
	v_ashrrev_i32_e32 v107, 31, v106
	v_ashrrev_i32_e32 v105, 31, v104
	v_lshlrev_b64 v[98:99], 12, v[100:101]
	v_lshlrev_b64 v[100:101], 12, v[102:103]
	global_load_dword v80, v[80:81], off nt
	s_nop 0
	global_load_dword v81, v[86:87], off nt
	v_lshl_add_u64 v[86:87], v[34:35], 0, v[96:97]
	v_lshl_add_u64 v[88:89], v[34:35], 0, v[94:95]
	v_lshlrev_b64 v[126:127], 12, v[104:105]
	v_lshlrev_b64 v[90:91], 12, v[106:107]
	global_load_dword v86, v[86:87], off nt
	s_nop 0
	global_load_dword v87, v[88:89], off nt
	v_lshl_add_u64 v[88:89], v[34:35], 0, v[100:101]
	v_lshl_add_u64 v[92:93], v[34:35], 0, v[98:99]
	v_lshlrev_b64 v[124:125], 2, v[102:103]
	v_lshlrev_b64 v[94:95], 2, v[106:107]
	global_load_dword v88, v[88:89], off nt
	s_nop 0
	global_load_dword v89, v[92:93], off nt
	v_lshlrev_b64 v[98:99], 2, v[104:105]
	v_lshl_add_u64 v[90:91], v[34:35], 0, v[90:91]
	v_lshl_add_u64 v[92:93], v[34:35], 0, v[126:127]
	global_load_dword v90, v[90:91], off nt
	s_nop 0
	global_load_dword v91, v[92:93], off nt
	v_lshl_add_u64 v[92:93], s[18:19], 0, v[94:95]
	v_lshl_add_u64 v[94:95], s[20:21], 0, v[94:95]
	v_lshl_add_u64 v[96:97], s[18:19], 0, v[98:99]
	v_lshl_add_u64 v[98:99], s[20:21], 0, v[98:99]
	v_cmp_gt_i32_e64 s[12:13], s75, v104
	v_lshl_add_u64 v[104:105], s[20:21], 0, v[124:125]
	v_lshl_add_u64 v[94:95], v[94:95], 0, s[58:59]
	v_cmp_gt_i32_e32 vcc, s75, v106
	v_lshl_add_u64 v[98:99], v[98:99], 0, s[58:59]
	v_lshl_add_u64 v[100:101], s[18:19], 0, v[124:125]
	v_lshl_add_u64 v[104:105], v[104:105], 0, s[58:59]
	v_cmp_gt_i32_e64 s[14:15], s75, v102
	v_cndmask_b32_e64 v97, v99, v97, s[12:13]
	v_cndmask_b32_e64 v96, v98, v96, s[12:13]
	v_cndmask_b32_e64 v101, v105, v101, s[14:15]
	v_cndmask_b32_e64 v100, v104, v100, s[14:15]
	v_cndmask_b32_e32 v93, v95, v93, vcc
	v_cndmask_b32_e32 v92, v94, v92, vcc
	global_load_dword v52, v[52:53], off nt
	s_nop 0
	global_load_dword v53, v[50:51], off nt
	s_nop 0
	global_load_dword v50, v[56:57], off nt
	global_load_dword v51, v[54:55], off nt
	s_nop 0
	global_load_dword v54, v[60:61], off nt
	global_load_dword v55, v[58:59], off nt
	global_load_dword v56, v[64:65], off nt
	global_load_dword v57, v[62:63], off nt
	s_nop 0
	global_load_dword v58, v[68:69], off nt
	global_load_dword v59, v[66:67], off nt
	global_load_dword v60, v[72:73], off nt
	global_load_dword v61, v[70:71], off nt
	global_load_dword v62, v[100:101], off nt
	global_load_dword v63, v[74:75], off nt
	global_load_dword v64, v[92:93], off nt
	global_load_dword v65, v[96:97], off nt
	s_add_i32 s62, s62, 16
	s_add_i32 s61, s61, 16
	s_add_i32 s63, s63, -16
	v_add_u32_e32 v66, s91, v2
	v_add_u32_e32 v68, s92, v3
	v_add_u32_e32 v72, s92, v5
	v_add_u32_e32 v70, s91, v20
	v_add_u32_e32 v92, s92, v9
	v_add_u32_e32 v74, s91, v22
	v_add_u32_e32 v96, s92, v21
	v_add_u32_e32 v94, s91, v24
	v_add_u32_e32 v98, s92, v23
	v_add_u32_e32 v99, s91, v26
	v_add_u32_e32 v100, s92, v25
	v_add_u32_e32 v101, s91, v28
	v_add_u32_e32 v102, s92, v27
	v_add_u32_e32 v103, s91, v30
	v_add_u32_e32 v104, s92, v29
	v_add_u32_e32 v105, s91, v32
	s_cmp_lg_u32 s63, 0
	v_mad_u64_u32 v[66:67], s[12:13], v66, s1, v[8:9]
	v_mad_u64_u32 v[68:69], s[12:13], v68, s1, v[8:9]
	v_mad_u64_u32 v[70:71], s[12:13], v70, s1, v[8:9]
	v_mad_u64_u32 v[72:73], s[12:13], v72, s1, v[8:9]
	v_mad_u64_u32 v[74:75], s[12:13], v74, s1, v[8:9]
	v_mad_u64_u32 v[92:93], s[12:13], v92, s1, v[8:9]
	v_mad_u64_u32 v[94:95], s[12:13], v94, s1, v[8:9]
	v_mad_u64_u32 v[96:97], s[12:13], v96, s1, v[8:9]
	s_waitcnt vmcnt(14)
	v_pk_mul_f32 v[52:53], v[84:85], v[52:53]
	v_mad_u64_u32 v[84:85], s[12:13], v99, s1, v[8:9]
	v_mad_u64_u32 v[98:99], s[12:13], v98, s1, v[8:9]
	s_waitcnt vmcnt(12)
	v_pk_mul_f32 v[50:51], v[76:77], v[50:51]
	v_mad_u64_u32 v[76:77], s[12:13], v101, s1, v[8:9]
	v_mad_u64_u32 v[100:101], s[12:13], v100, s1, v[8:9]
	s_waitcnt vmcnt(10)
	v_pk_mul_f32 v[54:55], v[78:79], v[54:55]
	v_mad_u64_u32 v[78:79], s[12:13], v103, s1, v[8:9]
	v_mad_u64_u32 v[102:103], s[12:13], v102, s1, v[8:9]
	s_waitcnt vmcnt(8)
	v_pk_mul_f32 v[56:57], v[82:83], v[56:57]
	v_mad_u64_u32 v[82:83], s[12:13], v105, s1, v[8:9]
	v_mad_u64_u32 v[104:105], s[12:13], v104, s1, v[8:9]
	s_waitcnt vmcnt(6)
	v_pk_mul_f32 v[58:59], v[80:81], v[58:59]
	s_waitcnt vmcnt(4)
	v_pk_mul_f32 v[60:61], v[86:87], v[60:61]
	s_waitcnt vmcnt(2)
	v_pk_mul_f32 v[62:63], v[88:89], v[62:63]
	s_waitcnt vmcnt(0)
	v_pk_mul_f32 v[64:65], v[90:91], v[64:65]
	ds_write_b32 v66, v52
	ds_write_b32 v68, v53
	ds_write_b32 v70, v50
	ds_write_b32 v72, v51
	ds_write_b32 v74, v54
	ds_write_b32 v92, v55
	ds_write_b32 v94, v56
	ds_write_b32 v96, v57
	ds_write_b32 v84, v58
	ds_write_b32 v98, v59
	ds_write_b32 v76, v60
	ds_write_b32 v100, v61
	ds_write_b32 v78, v62
	ds_write_b32 v102, v63
	ds_write_b32 v82, v64
	ds_write_b32 v104, v65
	s_cbranch_scc1 .LBB0_92
; #define LAS __attribute__((address_space(3)))
; __device__ __forceinline__ unsigned cvtpk(float lo, float hi) { f32x2 v = {lo, hi}; bf16x2_t b = __builtin_convertvector(v, bf16x2_t); return __builtin_bit_cast(unsigned, b); }
; template <int MODE>
; __device__ __forceinline__ void transpose_item(const float* __restrict__ W, int K, int N, bf16_t* __restrict__ WT, LAS float* scr, int item, int lane, const float* __restrict__ ga, const float* __restrict__ gb) {
;     ...
;     asm volatile("s_waitcnt lgkmcnt(0)" ::: "memory");
;     const int c = lane & 7;
; #pragma unroll
;     for (int j = 0; j < 4; ++j) { const int n = (lane >> 3) + 8 * j; const LAS float* s = scr + (8 * c) * 33 + n;
;         u32x4 o; o.x = cvtpk(s[0 * 33], s[1 * 33]); o.y = cvtpk(s[2 * 33], s[3 * 33]); o.z = cvtpk(s[4 * 33], s[5 * 33]); o.w = cvtpk(s[6 * 33], s[7 * 33]);
;         const int nn = n0 + n; int drow = nn;
;         if (MODE == 2) drow = 256 * (nn >> 7) + (nn & 127);
;         if (MODE == 3) drow = 256 * (nn >> 7) + 128 + (nn & 127);
;         *(u32x4*)(WT + (size_t)drow * K + k0 + 8 * c) = o; }
;     asm volatile("s_waitcnt lgkmcnt(0)" ::: "memory");
	s_waitcnt lgkmcnt(0)
	ds_read2_b32 v[38:39], v110 offset0:33 offset1:41
	ds_read2_b32 v[40:41], v110 offset1:8
	ds_read2_b32 v[42:43], v110 offset0:66 offset1:74
	ds_read2_b32 v[44:45], v110 offset0:99 offset1:107
	ds_read2_b32 v[46:47], v110 offset0:132 offset1:140
	ds_read2_b32 v[50:51], v110 offset0:165 offset1:173
	ds_read2_b32 v[52:53], v110 offset0:198 offset1:206
	ds_read2_b32 v[54:55], v110 offset0:231 offset1:239
	v_add_u32_e32 v58, s60, v109
	s_lshl_b32 s34, s34, 1
	v_ashrrev_i32_e32 v59, 31, v58
	v_lshl_add_u64 v[56:57], v[14:15], 0, s[34:35]
	v_lshlrev_b64 v[58:59], 11, v[58:59]
	s_waitcnt lgkmcnt(6)
	v_cvt_pk_bf16_f32 v34, v40, v38
	s_waitcnt lgkmcnt(4)
	v_cvt_pk_bf16_f32 v35, v42, v44
	s_waitcnt lgkmcnt(2)
	v_cvt_pk_bf16_f32 v36, v46, v50
	s_waitcnt lgkmcnt(0)
	v_cvt_pk_bf16_f32 v37, v52, v54
	v_lshl_add_u64 v[58:59], v[56:57], 0, v[58:59]
	v_add_u32_e32 v38, s60, v111
	global_store_dwordx4 v[58:59], v[34:37], off sc1
	s_nop 1
	v_cvt_pk_bf16_f32 v34, v41, v39
	v_ashrrev_i32_e32 v39, 31, v38
	v_cvt_pk_bf16_f32 v35, v43, v45
	v_cvt_pk_bf16_f32 v36, v47, v51
	v_cvt_pk_bf16_f32 v37, v53, v55
	v_lshlrev_b64 v[38:39], 11, v[38:39]
	ds_read2_b32 v[40:41], v110 offset0:49 offset1:57
	ds_read2_b32 v[42:43], v110 offset0:16 offset1:24
	ds_read2_b32 v[44:45], v110 offset0:82 offset1:90
	ds_read2_b32 v[46:47], v110 offset0:115 offset1:123
	ds_read2_b32 v[50:51], v110 offset0:148 offset1:156
	ds_read2_b32 v[52:53], v110 offset0:181 offset1:189
	ds_read2_b32 v[54:55], v110 offset0:214 offset1:222
	ds_read2_b32 v[58:59], v110 offset0:247 offset1:255
	v_lshl_add_u64 v[38:39], v[56:57], 0, v[38:39]
	global_store_dwordx4 v[38:39], v[34:37], off sc1
	v_add_u32_e32 v38, s60, v112
	v_ashrrev_i32_e32 v39, 31, v38
	v_lshlrev_b64 v[38:39], 11, v[38:39]
	s_waitcnt lgkmcnt(6)
	v_cvt_pk_bf16_f32 v34, v42, v40
	s_waitcnt lgkmcnt(4)
	v_cvt_pk_bf16_f32 v35, v44, v46
	s_waitcnt lgkmcnt(2)
	v_cvt_pk_bf16_f32 v36, v50, v52
	s_waitcnt lgkmcnt(0)
	v_cvt_pk_bf16_f32 v37, v54, v58
	v_lshl_add_u64 v[38:39], v[56:57], 0, v[38:39]
	global_store_dwordx4 v[38:39], v[34:37], off sc1
	v_add_u32_e32 v38, s60, v113
	v_ashrrev_i32_e32 v39, 31, v38
	v_lshlrev_b64 v[38:39], 11, v[38:39]
	v_cvt_pk_bf16_f32 v34, v43, v41
	v_cvt_pk_bf16_f32 v35, v45, v47
	v_cvt_pk_bf16_f32 v36, v51, v53
	v_cvt_pk_bf16_f32 v37, v55, v59
	v_lshl_add_u64 v[38:39], v[56:57], 0, v[38:39]
	global_store_dwordx4 v[38:39], v[34:37], off sc1
	s_waitcnt lgkmcnt(0)

; #define LAS __attribute__((address_space(3)))
; __device__ __forceinline__ unsigned cvtpk(float lo, float hi) { f32x2 v = {lo, hi}; bf16x2_t b = __builtin_convertvector(v, bf16x2_t); return __builtin_bit_cast(unsigned, b); }
; template <int MODE>
; __device__ __forceinline__ void transpose_item(const float* __restrict__ W, int K, int N, bf16_t* __restrict__ WT, LAS float* scr, int item, int lane, const float* __restrict__ ga, const float* __restrict__ gb) {
;     const int nblk = N / 32, kb = item / nblk, nb = item % nblk, k0 = 64 * kb, n0 = 32 * nb;
; #pragma unroll 8
;     for (int i = 0; i < 32; ++i) { const int kk = 2 * i + (lane >> 5); float v = W[(size_t)(k0 + kk) * N + n0 + (lane & 31)];
;         if (MODE == 1) { const int k = k0 + kk; v *= (k < 512) ? ga[k] : gb[k - 512]; }
;         scr[kk * 33 + (lane & 31)] = v; }
;     asm volatile("s_waitcnt lgkmcnt(0)" ::: "memory");
;     const int c = lane & 7;
; #pragma unroll
;     for (int j = 0; j < 4; ++j) { const int n = (lane >> 3) + 8 * j; const LAS float* s = scr + (8 * c) * 33 + n;
;         u32x4 o; o.x = cvtpk(s[0 * 33], s[1 * 33]); o.y = cvtpk(s[2 * 33], s[3 * 33]); o.z = cvtpk(s[4 * 33], s[5 * 33]); o.w = cvtpk(s[6 * 33], s[7 * 33]);
;         const int nn = n0 + n; int drow = nn;
;         if (MODE == 2) drow = 256 * (nn >> 7) + (nn & 127);
;         if (MODE == 3) drow = 256 * (nn >> 7) + 128 + (nn & 127);
;         *(u32x4*)(WT + (size_t)drow * K + k0 + 8 * c) = o; }
;     asm volatile("s_waitcnt lgkmcnt(0)" ::: "memory");
.LBB0_97:
	s_lshl_b32 s19, s15, 1
	s_lshl_b32 s34, s14, 1
	v_add_u32_e32 v50, s19, v6
	v_add_u32_e32 v52, s34, v31
	v_add_u32_e32 v56, s34, v33
	v_add_u32_e32 v54, s19, v36
	v_add_u32_e32 v60, s34, v37
	v_add_u32_e32 v58, s19, v38
	v_add_u32_e32 v64, s34, v39
	v_add_u32_e32 v62, s19, v40
	v_add_u32_e32 v68, s34, v41
	v_add_u32_e32 v66, s19, v42
	v_add_u32_e32 v72, s34, v43
	v_add_u32_e32 v70, s19, v44
	v_add_u32_e32 v76, s34, v45
	v_add_u32_e32 v74, s19, v46
	v_add_u32_e32 v80, s34, v47
	v_add_u32_e32 v78, s19, v48
	v_mad_i64_i32 v[50:51], s[20:21], v50, s76, v[34:35]
	v_mad_i64_i32 v[52:53], s[20:21], v52, s76, v[34:35]
	v_mad_i64_i32 v[54:55], s[20:21], v54, s76, v[34:35]
	v_mad_i64_i32 v[56:57], s[20:21], v56, s76, v[34:35]
	v_mad_i64_i32 v[58:59], s[20:21], v58, s76, v[34:35]
	v_mad_i64_i32 v[60:61], s[20:21], v60, s76, v[34:35]
	v_mad_i64_i32 v[62:63], s[20:21], v62, s76, v[34:35]
	v_mad_i64_i32 v[64:65], s[20:21], v64, s76, v[34:35]
	v_mad_i64_i32 v[66:67], s[20:21], v66, s76, v[34:35]
	v_mad_i64_i32 v[68:69], s[20:21], v68, s76, v[34:35]
	v_mad_i64_i32 v[70:71], s[20:21], v70, s76, v[34:35]
	v_mad_i64_i32 v[72:73], s[20:21], v72, s76, v[34:35]
	v_mad_i64_i32 v[74:75], s[20:21], v74, s76, v[34:35]
	v_mad_i64_i32 v[76:77], s[20:21], v76, s76, v[34:35]
	v_mad_i64_i32 v[78:79], s[20:21], v78, s76, v[34:35]
	v_mad_i64_i32 v[80:81], s[20:21], v80, s76, v[34:35]
	global_load_dword v82, v[50:51], off nt
	global_load_dword v83, v[52:53], off nt
	global_load_dword v84, v[54:55], off nt
	global_load_dword v85, v[56:57], off nt
	global_load_dword v86, v[58:59], off nt
	global_load_dword v87, v[60:61], off nt
	global_load_dword v88, v[62:63], off nt
	global_load_dword v89, v[64:65], off nt
	global_load_dword v90, v[66:67], off nt
	global_load_dword v91, v[68:69], off nt
	global_load_dword v92, v[70:71], off nt
	global_load_dword v93, v[72:73], off nt
	global_load_dword v94, v[74:75], off nt
	global_load_dword v95, v[76:77], off nt
	global_load_dword v96, v[78:79], off nt
	global_load_dword v97, v[80:81], off nt
	s_add_i32 s15, s15, 16
	s_add_i32 s14, s14, 16
	s_add_i32 s18, s18, -16
	v_add_u32_e32 v50, s19, v2
	v_add_u32_e32 v52, s34, v3
	v_add_u32_e32 v56, s34, v5
	v_add_u32_e32 v54, s19, v20
	v_add_u32_e32 v60, s34, v9
	v_add_u32_e32 v58, s19, v22
	v_add_u32_e32 v64, s34, v21
	v_add_u32_e32 v62, s19, v24
	v_add_u32_e32 v68, s34, v23
	v_add_u32_e32 v66, s19, v26
	v_add_u32_e32 v72, s34, v25
	v_add_u32_e32 v70, s19, v28
	v_add_u32_e32 v76, s34, v27
	v_add_u32_e32 v74, s19, v30
	v_add_u32_e32 v80, s34, v29
	v_add_u32_e32 v78, s19, v32
	s_cmp_lg_u32 s18, 0
	v_mad_u64_u32 v[50:51], s[20:21], v50, s1, v[8:9]
	v_mad_u64_u32 v[52:53], s[20:21], v52, s1, v[8:9]
	v_mad_u64_u32 v[54:55], s[20:21], v54, s1, v[8:9]
	v_mad_u64_u32 v[56:57], s[20:21], v56, s1, v[8:9]
	v_mad_u64_u32 v[58:59], s[20:21], v58, s1, v[8:9]
	v_mad_u64_u32 v[60:61], s[20:21], v60, s1, v[8:9]
	v_mad_u64_u32 v[62:63], s[20:21], v62, s1, v[8:9]
	v_mad_u64_u32 v[64:65], s[20:21], v64, s1, v[8:9]
	v_mad_u64_u32 v[66:67], s[20:21], v66, s1, v[8:9]
	v_mad_u64_u32 v[68:69], s[20:21], v68, s1, v[8:9]
	v_mad_u64_u32 v[70:71], s[20:21], v70, s1, v[8:9]
	v_mad_u64_u32 v[72:73], s[20:21], v72, s1, v[8:9]
	v_mad_u64_u32 v[74:75], s[20:21], v74, s1, v[8:9]
	v_mad_u64_u32 v[76:77], s[20:21], v76, s1, v[8:9]
	v_mad_u64_u32 v[78:79], s[20:21], v78, s1, v[8:9]
	v_mad_u64_u32 v[80:81], s[20:21], v80, s1, v[8:9]
	s_waitcnt vmcnt(15)
	ds_write_b32 v50, v82
	s_waitcnt vmcnt(14)
	ds_write_b32 v52, v83
	s_waitcnt vmcnt(13)
	ds_write_b32 v54, v84
	s_waitcnt vmcnt(12)
	ds_write_b32 v56, v85
	s_waitcnt vmcnt(11)
	ds_write_b32 v58, v86
	s_waitcnt vmcnt(10)
	ds_write_b32 v60, v87
	s_waitcnt vmcnt(9)
	ds_write_b32 v62, v88
	s_waitcnt vmcnt(8)
	ds_write_b32 v64, v89
	s_waitcnt vmcnt(7)
	ds_write_b32 v66, v90
	s_waitcnt vmcnt(6)
	ds_write_b32 v68, v91
	s_waitcnt vmcnt(5)
	ds_write_b32 v70, v92
	s_waitcnt vmcnt(4)
	ds_write_b32 v72, v93
	s_waitcnt vmcnt(3)
	ds_write_b32 v74, v94
	s_waitcnt vmcnt(2)
	ds_write_b32 v76, v95
	s_waitcnt vmcnt(1)
	ds_write_b32 v78, v96
	s_waitcnt vmcnt(0)
	ds_write_b32 v80, v97
	s_cbranch_scc1 .LBB0_97
	s_waitcnt lgkmcnt(0)
	ds_read2_b32 v[38:39], v110 offset0:33 offset1:41
	ds_read2_b32 v[40:41], v110 offset1:8
	ds_read2_b32 v[42:43], v110 offset0:66 offset1:74
	ds_read2_b32 v[44:45], v110 offset0:99 offset1:107
	ds_read2_b32 v[46:47], v110 offset0:132 offset1:140
	ds_read2_b32 v[50:51], v110 offset0:165 offset1:173
	ds_read2_b32 v[52:53], v110 offset0:198 offset1:206
	ds_read2_b32 v[54:55], v110 offset0:231 offset1:239
	s_and_b32 s13, 0xffff, s13
	s_and_b32 s12, 0xffff, s12
	v_add_u32_e32 v58, s13, v109
	s_lshl_b32 s34, s12, 1
	v_ashrrev_i32_e32 v59, 31, v58
	v_lshl_add_u64 v[56:57], v[16:17], 0, s[34:35]
	v_lshlrev_b64 v[58:59], 11, v[58:59]
	s_waitcnt lgkmcnt(6)
	v_cvt_pk_bf16_f32 v34, v40, v38
	s_waitcnt lgkmcnt(4)
	v_cvt_pk_bf16_f32 v35, v42, v44
	s_waitcnt lgkmcnt(2)
	v_cvt_pk_bf16_f32 v36, v46, v50
	s_waitcnt lgkmcnt(0)
	v_cvt_pk_bf16_f32 v37, v52, v54
	v_lshl_add_u64 v[58:59], v[56:57], 0, v[58:59]
	v_add_u32_e32 v38, s13, v111
	global_store_dwordx4 v[58:59], v[34:37], off sc1
	s_nop 1
	v_cvt_pk_bf16_f32 v34, v41, v39
	v_ashrrev_i32_e32 v39, 31, v38
	v_cvt_pk_bf16_f32 v35, v43, v45
	v_cvt_pk_bf16_f32 v36, v47, v51
	v_cvt_pk_bf16_f32 v37, v53, v55
	v_lshlrev_b64 v[38:39], 11, v[38:39]
	ds_read2_b32 v[40:41], v110 offset0:49 offset1:57
	ds_read2_b32 v[42:43], v110 offset0:16 offset1:24
	ds_read2_b32 v[44:45], v110 offset0:82 offset1:90
	ds_read2_b32 v[46:47], v110 offset0:115 offset1:123
	ds_read2_b32 v[50:51], v110 offset0:148 offset1:156
	ds_read2_b32 v[52:53], v110 offset0:181 offset1:189
	ds_read2_b32 v[54:55], v110 offset0:214 offset1:222
	ds_read2_b32 v[58:59], v110 offset0:247 offset1:255
	v_lshl_add_u64 v[38:39], v[56:57], 0, v[38:39]
	global_store_dwordx4 v[38:39], v[34:37], off sc1
	v_add_u32_e32 v38, s13, v112
	v_ashrrev_i32_e32 v39, 31, v38
	v_lshlrev_b64 v[38:39], 11, v[38:39]
	s_waitcnt lgkmcnt(6)
	v_cvt_pk_bf16_f32 v34, v42, v40
	s_waitcnt lgkmcnt(4)
	v_cvt_pk_bf16_f32 v35, v44, v46
	s_waitcnt lgkmcnt(2)
	v_cvt_pk_bf16_f32 v36, v50, v52
	s_waitcnt lgkmcnt(0)
	v_cvt_pk_bf16_f32 v37, v54, v58
	v_lshl_add_u64 v[38:39], v[56:57], 0, v[38:39]
	global_store_dwordx4 v[38:39], v[34:37], off sc1
	v_add_u32_e32 v38, s13, v113
	v_ashrrev_i32_e32 v39, 31, v38
	v_lshlrev_b64 v[38:39], 11, v[38:39]
	v_cvt_pk_bf16_f32 v34, v43, v41
	v_cvt_pk_bf16_f32 v35, v45, v47
	v_cvt_pk_bf16_f32 v36, v51, v53
	v_cvt_pk_bf16_f32 v37, v55, v59
	v_lshl_add_u64 v[38:39], v[56:57], 0, v[38:39]
	global_store_dwordx4 v[38:39], v[34:37], off sc1
	s_waitcnt lgkmcnt(0)

; __global__ void __launch_bounds__(NWAVES * 64, 2) fwd_kernel(Args args_unused) {
;     ...
;                 for (int idx = lane; idx < 9 * 64; idx += 64) { const int bb = idx >> 6, kk = idx & 63; const float v = (bb < 8) ? cin[bb * DM + k0 + kk] : cc[k0 + kk]; scr[idx] = v / (1.0f + __expf(-v)); }
.LBB0_102:
	s_or_b64 exec, exec, s[20:21]
	global_load_dword v33, v[36:37], off nt
	s_movk_i32 s20, 0x1ff
	v_add_u32_e32 v37, 64, v31
	v_cmp_lt_i32_e32 vcc, s20, v31
	s_or_b64 s[18:19], vcc, s[18:19]
	s_waitcnt vmcnt(0)
	v_mul_f32_e32 v36, 0xbfb8aa3b, v33
	v_exp_f32_e32 v36, v36
	s_nop 0
	v_add_f32_e32 v31, 1.0, v36
	v_div_scale_f32 v36, s[20:21], v31, v31, v33
	s_waitcnt lgkmcnt(2)
	v_rcp_f32_e32 v38, v36
	s_waitcnt lgkmcnt(1)
	v_div_scale_f32 v39, vcc, v33, v31, v33
	s_waitcnt lgkmcnt(0)
	v_fma_f32 v40, -v36, v38, 1.0
	v_fmac_f32_e32 v38, v40, v38
	v_mul_f32_e32 v40, v39, v38
	v_fma_f32 v41, -v36, v40, v39
	v_fmac_f32_e32 v40, v41, v38
	v_fma_f32 v36, -v36, v40, v39
	v_div_fmas_f32 v36, v36, v38, v40
	v_div_fixup_f32 v31, v36, v31, v33
	ds_write_b32 v6, v31
	v_add_u32_e32 v6, 0x100, v6
	v_mov_b32_e32 v31, v37
	s_andn2_b64 exec, exec, s[18:19]
	s_cbranch_execz .LBB0_105

; #define ARGP(i) ka_ptr(ka, (i) * 8)
; __global__ void __launch_bounds__(NWAVES * 64, 2) fwd_kernel(Args args_unused) {
;     ...
;                 float a0 = 0.f, a1 = 0.f, a2 = 0.f, a3 = 0.f, a4 = 0.f, a5 = 0.f, a6 = 0.f, a7 = 0.f, a8 = 0.f;
;                 const float* wp = ARGP(I_WMOD) + (size_t)k0 * NMOD + col;
; #pragma unroll 16
;                 for (int kk = 0; kk < 64; ++kk) { const float w = wp[(size_t)kk * NMOD];
;                     a0 += scr[kk] * w; a1 += scr[64 + kk] * w; a2 += scr[128 + kk] * w; a3 += scr[192 + kk] * w; a4 += scr[256 + kk] * w; a5 += scr[320 + kk] * w; a6 += scr[384 + kk] * w; a7 += scr[448 + kk] * w; a8 += scr[512 + kk] * w; }
.LBB0_106:
	v_lshl_add_u64 v[46:47], v[36:37], 0, s[12:13]
	s_movk_i32 s15, 0x6000
	v_add_co_u32_e32 v106, vcc, s15, v46
	s_mov_b32 s18, 0xc000
	s_nop 0
	v_addc_co_u32_e32 v107, vcc, 0, v47, vcc
	v_add_co_u32_e32 v212, vcc, s18, v46
	global_load_dword v48, v[46:47], off nt
	s_nop 0
	v_addc_co_u32_e32 v213, vcc, 0, v47, vcc
	v_add_co_u32_e32 v214, vcc, s77, v46
	v_mov_b32_e32 v31, s14
	s_nop 0
	v_addc_co_u32_e32 v215, vcc, 0, v47, vcc
	v_add_co_u32_e32 v216, vcc, s78, v46
	ds_read_b128 v[50:53], v31
	ds_read_b128 v[54:57], v31 offset:16
	ds_read_b128 v[58:61], v31 offset:32
	ds_read_b128 v[62:65], v31 offset:48
	v_addc_co_u32_e32 v217, vcc, 0, v47, vcc
	v_add_co_u32_e32 v218, vcc, s79, v46
	ds_read_b128 v[66:69], v31 offset:256
	ds_read_b128 v[70:73], v31 offset:272
	ds_read_b128 v[74:77], v31 offset:512
	ds_read_b128 v[78:81], v31 offset:528
	ds_read_b128 v[82:85], v31 offset:768
	ds_read_b128 v[86:89], v31 offset:784
	ds_read_b128 v[90:93], v31 offset:1024
	ds_read_b128 v[94:97], v31 offset:1040
	ds_read_b128 v[98:101], v31 offset:1280
	ds_read_b128 v[102:105], v31 offset:1296
	ds_read_b128 v[124:127], v31 offset:1536
	ds_read_b128 v[128:131], v31 offset:1552
	ds_read_b128 v[132:135], v31 offset:1792
	ds_read_b128 v[136:139], v31 offset:1808
	ds_read_b128 v[140:143], v31 offset:2048
	ds_read_b128 v[144:147], v31 offset:2064
	v_addc_co_u32_e32 v219, vcc, 0, v47, vcc
	v_add_co_u32_e32 v220, vcc, s80, v46
	ds_read_b128 v[148:151], v31 offset:288
	ds_read_b128 v[152:155], v31 offset:304
	ds_read_b128 v[156:159], v31 offset:544
	ds_read_b128 v[160:163], v31 offset:560
	ds_read_b128 v[164:167], v31 offset:800
	ds_read_b128 v[168:171], v31 offset:816
	ds_read_b128 v[172:175], v31 offset:1056
	ds_read_b128 v[176:179], v31 offset:1072
	ds_read_b128 v[180:183], v31 offset:1312
	ds_read_b128 v[184:187], v31 offset:1328
	ds_read_b128 v[188:191], v31 offset:1568
	ds_read_b128 v[192:195], v31 offset:1584
	ds_read_b128 v[196:199], v31 offset:1824
	ds_read_b128 v[200:203], v31 offset:1840
	ds_read_b128 v[204:207], v31 offset:2080
	ds_read_b128 v[208:211], v31 offset:2096
	v_addc_co_u32_e32 v221, vcc, 0, v47, vcc
	v_add_co_u32_e32 v222, vcc, s81, v46
	s_waitcnt lgkmcnt(14)
	v_mov_b32_e32 v238, v50
	v_addc_co_u32_e32 v223, vcc, 0, v47, vcc
	v_add_co_u32_e32 v224, vcc, s82, v46
	v_mov_b32_e32 v239, v66
	s_nop 0
	v_addc_co_u32_e32 v225, vcc, 0, v47, vcc
	v_add_co_u32_e32 v226, vcc, s83, v46
	v_mov_b32_e32 v240, v74
	s_nop 0
	v_addc_co_u32_e32 v227, vcc, 0, v47, vcc
	v_add_co_u32_e32 v228, vcc, s84, v46
	v_mov_b32_e32 v241, v82
	s_nop 0
	v_addc_co_u32_e32 v229, vcc, 0, v47, vcc
	v_add_co_u32_e32 v230, vcc, s85, v46
	v_mov_b32_e32 v242, v90
	s_nop 0
	v_addc_co_u32_e32 v231, vcc, 0, v47, vcc
	v_add_co_u32_e32 v232, vcc, s86, v46
	v_mov_b32_e32 v243, v98
	s_nop 0
	v_addc_co_u32_e32 v233, vcc, 0, v47, vcc
	v_add_co_u32_e32 v234, vcc, s87, v46
	v_mov_b32_e32 v244, v124
	s_nop 0
	v_addc_co_u32_e32 v235, vcc, 0, v47, vcc
	v_add_co_u32_e32 v236, vcc, s88, v46
	v_mov_b32_e32 v245, v132
	s_nop 0
	v_addc_co_u32_e32 v237, vcc, 0, v47, vcc
	v_add_co_u32_e32 v46, vcc, s89, v46
	v_mov_b32_e32 v66, v51
	s_nop 0
	v_addc_co_u32_e32 v47, vcc, 0, v47, vcc
	global_load_dword v106, v[106:107], off nt
	s_nop 0
	global_load_dword v212, v[212:213], off nt
	s_nop 0
	global_load_dword v214, v[214:215], off nt
	s_nop 0
	global_load_dword v216, v[216:217], off nt
	s_nop 0
	global_load_dword v218, v[218:219], off nt
	s_nop 0
	global_load_dword v220, v[220:221], off nt
	s_nop 0
	global_load_dword v222, v[222:223], off nt
	s_nop 0
	global_load_dword v224, v[224:225], off nt
	s_nop 0
	global_load_dword v226, v[226:227], off nt
	s_nop 0
	global_load_dword v228, v[228:229], off nt
	s_nop 0
	global_load_dword v230, v[230:231], off nt
	s_nop 0
	global_load_dword v232, v[232:233], off nt
	s_nop 0
	global_load_dword v234, v[234:235], off nt
	s_nop 0
	global_load_dword v236, v[236:237], off nt
	s_nop 0
	global_load_dword v46, v[46:47], off nt
	v_mov_b32_e32 v82, v75
	v_mov_b32_e32 v98, v91
	v_mov_b32_e32 v132, v125
	v_mov_b32_e32 v50, v52
	v_mov_b32_e32 v51, v68
	v_mov_b32_e32 v74, v76
	v_mov_b32_e32 v75, v84
	v_mov_b32_e32 v90, v92
	v_mov_b32_e32 v91, v100
	v_mov_b32_e32 v124, v126
	v_mov_b32_e32 v125, v134
	s_waitcnt vmcnt(15)
	v_pk_fma_f32 v[44:45], v[48:49], v[238:239], v[44:45] op_sel_hi:[0,1,1]
	v_pk_fma_f32 v[42:43], v[48:49], v[240:241], v[42:43] op_sel_hi:[0,1,1]
	v_pk_fma_f32 v[40:41], v[48:49], v[242:243], v[40:41] op_sel_hi:[0,1,1]
	v_pk_fma_f32 v[38:39], v[48:49], v[244:245], v[38:39] op_sel_hi:[0,1,1]
	v_fmac_f32_e32 v6, v48, v140
	v_mov_b32_e32 v68, v53
	v_mov_b32_e32 v84, v77
	v_mov_b32_e32 v100, v93
	v_mov_b32_e32 v134, v127
	v_mov_b32_e32 v52, v54
	v_mov_b32_e32 v53, v70
	v_mov_b32_e32 v76, v78
	v_mov_b32_e32 v77, v86
	v_mov_b32_e32 v92, v94
	v_mov_b32_e32 v93, v102
	v_mov_b32_e32 v126, v128
	v_mov_b32_e32 v127, v136
	v_mov_b32_e32 v70, v55
	v_mov_b32_e32 v86, v79
	v_mov_b32_e32 v102, v95
	v_mov_b32_e32 v136, v129
	v_mov_b32_e32 v54, v56
	v_mov_b32_e32 v55, v72
	v_mov_b32_e32 v78, v80
	v_mov_b32_e32 v79, v88
	v_mov_b32_e32 v94, v96
	v_mov_b32_e32 v95, v104
	v_mov_b32_e32 v128, v130
	v_mov_b32_e32 v129, v138
	v_mov_b32_e32 v72, v57
	v_mov_b32_e32 v88, v81
	v_mov_b32_e32 v104, v97
	v_mov_b32_e32 v138, v131
	v_mov_b32_e32 v56, v58
	v_mov_b32_e32 v57, v148
	s_waitcnt lgkmcnt(13)
	v_mov_b32_e32 v80, v156
	s_waitcnt lgkmcnt(11)
	v_mov_b32_e32 v81, v164
	s_waitcnt lgkmcnt(9)
	v_mov_b32_e32 v96, v172
	s_waitcnt lgkmcnt(7)
	v_mov_b32_e32 v97, v180
	s_waitcnt lgkmcnt(5)
	v_mov_b32_e32 v130, v188
	s_waitcnt lgkmcnt(3)
; #define ARGP(i) ka_ptr(ka, (i) * 8)
; __global__ void __launch_bounds__(NWAVES * 64, 2) fwd_kernel(Args args_unused) {
;     ...
;                 for (int kk = 0; kk < 64; ++kk) { const float w = wp[(size_t)kk * NMOD];
;                     a0 += scr[kk] * w; a1 += scr[64 + kk] * w; a2 += scr[128 + kk] * w; a3 += scr[192 + kk] * w; a4 += scr[256 + kk] * w; a5 += scr[320 + kk] * w; a6 += scr[384 + kk] * w; a7 += scr[448 + kk] * w; a8 += scr[512 + kk] * w; }
;                 const float bm = (kc == 0) ? ARGP(I_BMOD)[col] : 0.f;
	v_mov_b32_e32 v131, v196
	v_mov_b32_e32 v148, v59
	v_mov_b32_e32 v164, v157
	v_mov_b32_e32 v180, v173
	v_mov_b32_e32 v196, v189
	v_mov_b32_e32 v58, v60
	v_mov_b32_e32 v59, v150
	v_mov_b32_e32 v156, v158
	v_mov_b32_e32 v157, v166
	v_mov_b32_e32 v172, v174
	v_mov_b32_e32 v173, v182
	v_mov_b32_e32 v188, v190
	v_mov_b32_e32 v189, v198
	v_mov_b32_e32 v150, v61
	s_waitcnt vmcnt(14)
	v_pk_fma_f32 v[44:45], v[106:107], v[66:67], v[44:45] op_sel_hi:[0,1,1]
	v_pk_fma_f32 v[42:43], v[106:107], v[82:83], v[42:43] op_sel_hi:[0,1,1]
	v_pk_fma_f32 v[40:41], v[106:107], v[98:99], v[40:41] op_sel_hi:[0,1,1]
	v_pk_fma_f32 v[38:39], v[106:107], v[132:133], v[38:39] op_sel_hi:[0,1,1]
	v_fmac_f32_e32 v6, v106, v141
	s_waitcnt vmcnt(13)
	v_pk_fma_f32 v[44:45], v[212:213], v[50:51], v[44:45] op_sel_hi:[0,1,1]
	v_pk_fma_f32 v[42:43], v[212:213], v[74:75], v[42:43] op_sel_hi:[0,1,1]
	v_pk_fma_f32 v[40:41], v[212:213], v[90:91], v[40:41] op_sel_hi:[0,1,1]
	v_pk_fma_f32 v[38:39], v[212:213], v[124:125], v[38:39] op_sel_hi:[0,1,1]
	v_fmac_f32_e32 v6, v212, v142
	s_waitcnt vmcnt(12)
	v_pk_fma_f32 v[44:45], v[214:215], v[68:69], v[44:45] op_sel_hi:[0,1,1]
	v_pk_fma_f32 v[42:43], v[214:215], v[84:85], v[42:43] op_sel_hi:[0,1,1]
	v_pk_fma_f32 v[40:41], v[214:215], v[100:101], v[40:41] op_sel_hi:[0,1,1]
	v_pk_fma_f32 v[38:39], v[214:215], v[134:135], v[38:39] op_sel_hi:[0,1,1]
	v_fmac_f32_e32 v6, v214, v143
	s_waitcnt vmcnt(11)
	v_pk_fma_f32 v[44:45], v[216:217], v[52:53], v[44:45] op_sel_hi:[0,1,1]
	v_pk_fma_f32 v[42:43], v[216:217], v[76:77], v[42:43] op_sel_hi:[0,1,1]
	v_pk_fma_f32 v[40:41], v[216:217], v[92:93], v[40:41] op_sel_hi:[0,1,1]
	v_pk_fma_f32 v[38:39], v[216:217], v[126:127], v[38:39] op_sel_hi:[0,1,1]
	v_fmac_f32_e32 v6, v216, v144
	s_waitcnt vmcnt(10)
	v_pk_fma_f32 v[44:45], v[218:219], v[70:71], v[44:45] op_sel_hi:[0,1,1]
	v_pk_fma_f32 v[42:43], v[218:219], v[86:87], v[42:43] op_sel_hi:[0,1,1]
	v_pk_fma_f32 v[40:41], v[218:219], v[102:103], v[40:41] op_sel_hi:[0,1,1]
	v_pk_fma_f32 v[38:39], v[218:219], v[136:137], v[38:39] op_sel_hi:[0,1,1]
	v_fmac_f32_e32 v6, v218, v145
	s_waitcnt vmcnt(9)
	v_pk_fma_f32 v[44:45], v[220:221], v[54:55], v[44:45] op_sel_hi:[0,1,1]
	v_pk_fma_f32 v[42:43], v[220:221], v[78:79], v[42:43] op_sel_hi:[0,1,1]
	v_pk_fma_f32 v[40:41], v[220:221], v[94:95], v[40:41] op_sel_hi:[0,1,1]
	v_pk_fma_f32 v[38:39], v[220:221], v[128:129], v[38:39] op_sel_hi:[0,1,1]
	v_fmac_f32_e32 v6, v220, v146
	s_waitcnt vmcnt(8)
	v_pk_fma_f32 v[44:45], v[222:223], v[72:73], v[44:45] op_sel_hi:[0,1,1]
	v_pk_fma_f32 v[42:43], v[222:223], v[88:89], v[42:43] op_sel_hi:[0,1,1]
	v_pk_fma_f32 v[40:41], v[222:223], v[104:105], v[40:41] op_sel_hi:[0,1,1]
	v_pk_fma_f32 v[38:39], v[222:223], v[138:139], v[38:39] op_sel_hi:[0,1,1]
	v_fmac_f32_e32 v6, v222, v147
	s_waitcnt vmcnt(7)
	v_pk_fma_f32 v[44:45], v[224:225], v[56:57], v[44:45] op_sel_hi:[0,1,1]
	v_pk_fma_f32 v[42:43], v[224:225], v[80:81], v[42:43] op_sel_hi:[0,1,1]
	v_pk_fma_f32 v[40:41], v[224:225], v[96:97], v[40:41] op_sel_hi:[0,1,1]
	v_pk_fma_f32 v[38:39], v[224:225], v[130:131], v[38:39] op_sel_hi:[0,1,1]
	s_waitcnt lgkmcnt(1)
	v_fmac_f32_e32 v6, v224, v204
	s_waitcnt vmcnt(6)
	v_pk_fma_f32 v[44:45], v[226:227], v[148:149], v[44:45] op_sel_hi:[0,1,1]
	v_pk_fma_f32 v[42:43], v[226:227], v[164:165], v[42:43] op_sel_hi:[0,1,1]
	v_pk_fma_f32 v[40:41], v[226:227], v[180:181], v[40:41] op_sel_hi:[0,1,1]
	v_pk_fma_f32 v[38:39], v[226:227], v[196:197], v[38:39] op_sel_hi:[0,1,1]
	v_fmac_f32_e32 v6, v226, v205
	v_mov_b32_e32 v166, v159
	v_mov_b32_e32 v182, v175
	v_mov_b32_e32 v198, v191
	s_waitcnt vmcnt(5)
	v_pk_fma_f32 v[44:45], v[228:229], v[58:59], v[44:45] op_sel_hi:[0,1,1]
	v_pk_fma_f32 v[42:43], v[228:229], v[156:157], v[42:43] op_sel_hi:[0,1,1]
	v_pk_fma_f32 v[40:41], v[228:229], v[172:173], v[40:41] op_sel_hi:[0,1,1]
	v_pk_fma_f32 v[38:39], v[228:229], v[188:189], v[38:39] op_sel_hi:[0,1,1]
	v_fmac_f32_e32 v6, v228, v206
	v_mov_b32_e32 v60, v62
	v_mov_b32_e32 v61, v152
	v_mov_b32_e32 v158, v160
	v_mov_b32_e32 v159, v168
	v_mov_b32_e32 v174, v176
	v_mov_b32_e32 v175, v184
	v_mov_b32_e32 v190, v192
	v_mov_b32_e32 v191, v200
	s_waitcnt vmcnt(4)
	v_pk_fma_f32 v[44:45], v[230:231], v[150:151], v[44:45] op_sel_hi:[0,1,1]
	v_pk_fma_f32 v[42:43], v[230:231], v[166:167], v[42:43] op_sel_hi:[0,1,1]
	v_pk_fma_f32 v[40:41], v[230:231], v[182:183], v[40:41] op_sel_hi:[0,1,1]
	v_pk_fma_f32 v[38:39], v[230:231], v[198:199], v[38:39] op_sel_hi:[0,1,1]
	v_fmac_f32_e32 v6, v230, v207
	v_mov_b32_e32 v152, v63
	v_mov_b32_e32 v168, v161
	v_mov_b32_e32 v184, v177
	v_mov_b32_e32 v200, v193
	s_waitcnt vmcnt(3)
	v_pk_fma_f32 v[44:45], v[232:233], v[60:61], v[44:45] op_sel_hi:[0,1,1]
	v_pk_fma_f32 v[42:43], v[232:233], v[158:159], v[42:43] op_sel_hi:[0,1,1]
	v_pk_fma_f32 v[40:41], v[232:233], v[174:175], v[40:41] op_sel_hi:[0,1,1]
	v_pk_fma_f32 v[38:39], v[232:233], v[190:191], v[38:39] op_sel_hi:[0,1,1]
	s_waitcnt lgkmcnt(0)
	v_fmac_f32_e32 v6, v232, v208
	s_add_u32 s12, s12, 0x60000
	v_mov_b32_e32 v62, v64
	v_mov_b32_e32 v63, v154
	v_mov_b32_e32 v160, v162
	v_mov_b32_e32 v161, v170
	v_mov_b32_e32 v176, v178
	v_mov_b32_e32 v177, v186
	v_mov_b32_e32 v192, v194
	v_mov_b32_e32 v193, v202
	s_waitcnt vmcnt(2)
	v_pk_fma_f32 v[44:45], v[234:235], v[152:153], v[44:45] op_sel_hi:[0,1,1]
	v_pk_fma_f32 v[42:43], v[234:235], v[168:169], v[42:43] op_sel_hi:[0,1,1]
	v_pk_fma_f32 v[40:41], v[234:235], v[184:185], v[40:41] op_sel_hi:[0,1,1]
	v_pk_fma_f32 v[38:39], v[234:235], v[200:201], v[38:39] op_sel_hi:[0,1,1]
	v_fmac_f32_e32 v6, v234, v209
	s_addc_u32 s13, s13, 0
	s_add_i32 s14, s14, 64
	v_mov_b32_e32 v154, v65
	v_mov_b32_e32 v170, v163
	v_mov_b32_e32 v186, v179
	v_mov_b32_e32 v202, v195
	s_waitcnt vmcnt(1)
	v_pk_fma_f32 v[44:45], v[236:237], v[62:63], v[44:45] op_sel_hi:[0,1,1]
	v_pk_fma_f32 v[42:43], v[236:237], v[160:161], v[42:43] op_sel_hi:[0,1,1]
	v_pk_fma_f32 v[40:41], v[236:237], v[176:177], v[40:41] op_sel_hi:[0,1,1]
	v_pk_fma_f32 v[38:39], v[236:237], v[192:193], v[38:39] op_sel_hi:[0,1,1]
	v_fmac_f32_e32 v6, v236, v210
	s_cmp_eq_u32 s12, 0x180000
	s_waitcnt vmcnt(0)
	v_pk_fma_f32 v[44:45], v[46:47], v[154:155], v[44:45] op_sel_hi:[0,1,1]
	v_pk_fma_f32 v[42:43], v[46:47], v[170:171], v[42:43] op_sel_hi:[0,1,1]
	v_pk_fma_f32 v[40:41], v[46:47], v[186:187], v[40:41] op_sel_hi:[0,1,1]
	v_pk_fma_f32 v[38:39], v[46:47], v[202:203], v[38:39] op_sel_hi:[0,1,1]
	v_fmac_f32_e32 v6, v46, v211
	s_cbranch_scc0 .LBB0_106
	s_add_i32 s12, s90, 0x5f
	s_cmpk_lt_u32 s12, 0xbf
	v_mov_b32_e32 v31, 0
	s_cbranch_scc0 .LBB0_23
	s_load_dwordx2 s[12:13], s[96:97], 40
	s_waitcnt lgkmcnt(0)
	s_nop 0
	v_lshl_add_u64 v[36:37], v[34:35], 2, s[12:13]
	global_load_dword v31, v[36:37], off nt
	s_branch .LBB0_23
